# K-loop: s_setprio 1 after first MFMA, s_setprio 0 before last MFMA, loop-counter cmp into MFMA shadow, ds_reads issued before glds address SALU
# baseline (speedup 1.0000x reference)
; #define PG8_STAGE(bufoff, gbase, voff) do { _Pragma("unroll") for (int _i = 0; _i < 2; ++_i) \
;         __builtin_amdgcn_global_load_lds((const unsigned*)((const char*)(gbase) + (voff)[_i]), (LAS unsigned*)(lds + (bufoff) + ldsw + _i * 8192), 16, 0, 0); } while (0)
; #define PG8_LDA(dst, b, h) do { _Pragma("unroll") for (int m = 0; m < 4; ++m) _Pragma("unroll") for (int k = 0; k < 2; ++k) dst[m][k] = *(const LAS bf16x8*)(lds + PG8_SA(b, h) + aoff + m * 2048 + k * 1024); } while (0)
; #define PG8_LDB(dst, b, h) do { _Pragma("unroll") for (int n = 0; n < 2; ++n) _Pragma("unroll") for (int k = 0; k < 2; ++k) dst[n][k] = *(const LAS bf16x8*)(lds + PG8_SB(b, h) + boff + n * 2048 + k * 1024); } while (0)
; #define PG8_MMA(ai, bj, At, Bt) do { __builtin_amdgcn_s_setprio(1); _Pragma("unroll") for (int m = 0; m < 4; ++m) _Pragma("unroll") for (int n = 0; n < 2; ++n) _Pragma("unroll") for (int k = 0; k < 2; ++k) \
;         acc[ai][bj][m][n] = __builtin_amdgcn_mfma_f32_16x16x32_bf16(Bt[n][k], At[m][k], acc[ai][bj][m][n], 0, 0, 0); __builtin_amdgcn_s_setprio(0); } while (0)
; #define PG8_WAIT_L(n) asm volatile("s_waitcnt lgkmcnt(" #n ")" ::: "memory")
; #define PG8_BAR __builtin_amdgcn_s_barrier()
; #define PG8_SCHED __builtin_amdgcn_sched_barrier(0)
; template <class Epi>
; __device__ __forceinline__ void gemm_phase(LAS unsigned char* lds, const Gemm g, const StaticOrder& S, const Epi& E) {
;     ...
;             const bool last = (t == nt - 2);
;             const char* a1 = cA + (size_t)(t + 1) * kstep;
;             const char* a2 = last ? nA : cA + (size_t)(t + 2) * kstep; const char* b2 = last ? nB : cB + (size_t)(t + 2) * kstep;
;             const char* a3 = a2 + kstep; const char* b3 = b2 + kstep;
;             PG8_LDB(B0, 0, 0); PG8_SCHED; PG8_LDA(At, 0, 0); PG8_STAGE(PG8_SA(1, 1), a1 + hstepA, voffA);
;             PG8_WAIT_L(8); PG8_BAR; PG8_WAIT_L(0); PG8_MMA(0, 0, At, B0); PG8_BAR; PG8_SCHED;
;             PG8_LDB(B1, 0, 1); PG8_STAGE(PG8_SB(0, 0), b2, voffB);
;             PG8_BAR; PG8_WAIT_L(0); PG8_MMA(0, 1, At, B1); PG8_BAR;
;             PG8_LDA(At, 0, 1); PG8_STAGE(PG8_SA(0, 0), a2, voffA);
;             PG8_BAR; PG8_WAIT_L(0); PG8_MMA(1, 0, At, B0); PG8_BAR; PG8_SCHED;
.LBB0_141:
	s_mov_b32 s55, 0x10000
	v_add_u32_e32 v148, s55, v134
	ds_read_b128 v[136:139], v148
	ds_read_b128 v[140:143], v148 offset:1024
	ds_read_b128 v[144:147], v148 offset:2048
	ds_read_b128 v[148:151], v148 offset:3072
	ds_read_b128 v[156:159], v135
	ds_read_b128 v[160:163], v135 offset:1024
	ds_read_b128 v[164:167], v135 offset:2048
	ds_read_b128 v[168:171], v135 offset:3072
	ds_read_b128 v[172:175], v135 offset:4096
	ds_read_b128 v[176:179], v135 offset:5120
	ds_read_b128 v[180:183], v135 offset:6144
	ds_read_b128 v[184:187], v135 offset:7168
	s_add_u32 s24, s22, 0xfff84000
	s_addc_u32 s25, s23, -1
	s_cmp_eq_u32 s54, 28
	s_cselect_b32 s28, s49, s24
	s_cselect_b32 s29, s15, s25
	s_cselect_b32 s24, s50, s51
	s_cselect_b32 s25, s5, s52
	s_add_u32 s26, s28, 0x4000
	s_addc_u32 s27, s29, 0
	s_add_i32 m0, s37, 0xc000
	v_lshl_add_u64 v[188:189], s[22:23], 0, v[128:129]
	global_load_lds_dwordx4 v[188:189], off
	s_add_i32 m0, s37, 0xe000
	v_lshl_add_u64 v[188:189], s[22:23], 0, v[130:131]
	global_load_lds_dwordx4 v[188:189], off
	s_waitcnt lgkmcnt(8)
	s_barrier
	s_waitcnt lgkmcnt(0)
	v_mfma_f32_16x16x32_bf16 v[124:127], v[136:139], v[156:159], v[124:127]
	s_setprio 1
	v_mfma_f32_16x16x32_bf16 v[120:123], v[144:147], v[156:159], v[120:123]
	v_mfma_f32_16x16x32_bf16 v[108:111], v[136:139], v[164:167], v[108:111]
	v_mfma_f32_16x16x32_bf16 v[104:107], v[144:147], v[164:167], v[104:107]
	v_mfma_f32_16x16x32_bf16 v[92:95], v[136:139], v[172:175], v[92:95]
	v_mfma_f32_16x16x32_bf16 v[88:91], v[144:147], v[172:175], v[88:91]
	v_mfma_f32_16x16x32_bf16 v[76:79], v[136:139], v[180:183], v[76:79]
	v_mfma_f32_16x16x32_bf16 v[72:75], v[144:147], v[180:183], v[72:75]
	v_mfma_f32_16x16x32_bf16 v[124:127], v[140:143], v[160:163], v[124:127]
	v_mfma_f32_16x16x32_bf16 v[120:123], v[148:151], v[160:163], v[120:123]
	v_mfma_f32_16x16x32_bf16 v[108:111], v[140:143], v[168:171], v[108:111]
	v_mfma_f32_16x16x32_bf16 v[104:107], v[148:151], v[168:171], v[104:107]
	v_mfma_f32_16x16x32_bf16 v[92:95], v[140:143], v[176:179], v[92:95]
	v_mfma_f32_16x16x32_bf16 v[88:91], v[148:151], v[176:179], v[88:91]
	v_mfma_f32_16x16x32_bf16 v[76:79], v[140:143], v[184:187], v[76:79]
	s_setprio 0
	v_mfma_f32_16x16x32_bf16 v[72:75], v[148:151], v[184:187], v[72:75]
	s_barrier
	s_mov_b32 s58, 0x14000
	v_add_u32_e32 v152, s58, v134
	ds_read_b128 v[188:191], v152
	ds_read_b128 v[192:195], v152 offset:1024
	ds_read_b128 v[196:199], v152 offset:2048
	ds_read_b128 v[200:203], v152 offset:3072
	s_add_i32 s55, s55, s36
	s_mov_b32 m0, s55
	v_lshl_add_u64 v[204:205], s[24:25], 0, v[128:129]
	global_load_lds_dwordx4 v[204:205], off
	s_add_i32 m0, s55, 0x2000
	v_lshl_add_u64 v[204:205], s[24:25], 0, v[130:131]
	global_load_lds_dwordx4 v[204:205], off
	s_barrier
	s_waitcnt lgkmcnt(0)
	v_mfma_f32_16x16x32_bf16 v[116:119], v[188:191], v[156:159], v[116:119]
	s_setprio 1
	v_mfma_f32_16x16x32_bf16 v[112:115], v[196:199], v[156:159], v[112:115]
	s_mov_b32 m0, s37
	v_lshl_add_u64 v[204:205], s[28:29], 0, v[128:129]
	v_mfma_f32_16x16x32_bf16 v[100:103], v[188:191], v[164:167], v[100:103]
	v_mfma_f32_16x16x32_bf16 v[96:99], v[196:199], v[164:167], v[96:99]
	v_mfma_f32_16x16x32_bf16 v[84:87], v[188:191], v[172:175], v[84:87]
	v_mfma_f32_16x16x32_bf16 v[80:83], v[196:199], v[172:175], v[80:83]
	v_mfma_f32_16x16x32_bf16 v[68:71], v[188:191], v[180:183], v[68:71]
	v_mfma_f32_16x16x32_bf16 v[64:67], v[196:199], v[180:183], v[64:67]
	v_mfma_f32_16x16x32_bf16 v[116:119], v[192:195], v[160:163], v[116:119]
	v_mfma_f32_16x16x32_bf16 v[112:115], v[200:203], v[160:163], v[112:115]
	v_mfma_f32_16x16x32_bf16 v[100:103], v[192:195], v[168:171], v[100:103]
	v_mfma_f32_16x16x32_bf16 v[96:99], v[200:203], v[168:171], v[96:99]
	v_mfma_f32_16x16x32_bf16 v[84:87], v[192:195], v[176:179], v[84:87]
	v_mfma_f32_16x16x32_bf16 v[80:83], v[200:203], v[176:179], v[80:83]
	v_mfma_f32_16x16x32_bf16 v[68:71], v[192:195], v[184:187], v[68:71]
	s_setprio 0
	v_mfma_f32_16x16x32_bf16 v[64:67], v[200:203], v[184:187], v[64:67]
	s_barrier
	ds_read_b128 v[156:159], v135 offset:16384
	ds_read_b128 v[160:163], v135 offset:17408
	ds_read_b128 v[164:167], v135 offset:18432
	ds_read_b128 v[168:171], v135 offset:19456
	ds_read_b128 v[172:175], v135 offset:20480
	ds_read_b128 v[176:179], v135 offset:21504
	ds_read_b128 v[180:183], v135 offset:22528
	ds_read_b128 v[184:187], v135 offset:23552
	global_load_lds_dwordx4 v[204:205], off
	s_mov_b32 m0, s38
	v_lshl_add_u64 v[204:205], s[28:29], 0, v[130:131]
	global_load_lds_dwordx4 v[204:205], off
	s_barrier
	s_waitcnt lgkmcnt(0)
	v_mfma_f32_16x16x32_bf16 v[60:63], v[136:139], v[156:159], v[60:63]
	s_setprio 1
	v_mfma_f32_16x16x32_bf16 v[56:59], v[144:147], v[156:159], v[56:59]
	v_mfma_f32_16x16x32_bf16 v[44:47], v[136:139], v[164:167], v[44:47]
	v_mfma_f32_16x16x32_bf16 v[40:43], v[144:147], v[164:167], v[40:43]
	v_mfma_f32_16x16x32_bf16 v[28:31], v[136:139], v[172:175], v[28:31]
	v_mfma_f32_16x16x32_bf16 v[24:27], v[144:147], v[172:175], v[24:27]
	v_mfma_f32_16x16x32_bf16 v[12:15], v[136:139], v[180:183], v[12:15]
	v_mfma_f32_16x16x32_bf16 v[8:11], v[144:147], v[180:183], v[8:11]
	v_mfma_f32_16x16x32_bf16 v[60:63], v[140:143], v[160:163], v[60:63]
	v_mfma_f32_16x16x32_bf16 v[56:59], v[148:151], v[160:163], v[56:59]
	v_mfma_f32_16x16x32_bf16 v[44:47], v[140:143], v[168:171], v[44:47]
	v_mfma_f32_16x16x32_bf16 v[40:43], v[148:151], v[168:171], v[40:43]
	v_mfma_f32_16x16x32_bf16 v[28:31], v[140:143], v[176:179], v[28:31]
	v_mfma_f32_16x16x32_bf16 v[24:27], v[148:151], v[176:179], v[24:27]
	v_mfma_f32_16x16x32_bf16 v[12:15], v[140:143], v[184:187], v[12:15]
	s_setprio 0
	v_mfma_f32_16x16x32_bf16 v[8:11], v[148:151], v[184:187], v[8:11]
	s_barrier
; #define PG8_STAGE(bufoff, gbase, voff) do { _Pragma("unroll") for (int _i = 0; _i < 2; ++_i) \
;         __builtin_amdgcn_global_load_lds((const unsigned*)((const char*)(gbase) + (voff)[_i]), (LAS unsigned*)(lds + (bufoff) + ldsw + _i * 8192), 16, 0, 0); } while (0)
; #define PG8_LDA(dst, b, h) do { _Pragma("unroll") for (int m = 0; m < 4; ++m) _Pragma("unroll") for (int k = 0; k < 2; ++k) dst[m][k] = *(const LAS bf16x8*)(lds + PG8_SA(b, h) + aoff + m * 2048 + k * 1024); } while (0)
; #define PG8_LDB(dst, b, h) do { _Pragma("unroll") for (int n = 0; n < 2; ++n) _Pragma("unroll") for (int k = 0; k < 2; ++k) dst[n][k] = *(const LAS bf16x8*)(lds + PG8_SB(b, h) + boff + n * 2048 + k * 1024); } while (0)
; #define PG8_MMA(ai, bj, At, Bt) do { __builtin_amdgcn_s_setprio(1); _Pragma("unroll") for (int m = 0; m < 4; ++m) _Pragma("unroll") for (int n = 0; n < 2; ++n) _Pragma("unroll") for (int k = 0; k < 2; ++k) \
;         acc[ai][bj][m][n] = __builtin_amdgcn_mfma_f32_16x16x32_bf16(Bt[n][k], At[m][k], acc[ai][bj][m][n], 0, 0, 0); __builtin_amdgcn_s_setprio(0); } while (0)
; #define PG8_WAIT_V(n) asm volatile("s_waitcnt vmcnt(" #n ")" ::: "memory")
; #define PG8_WAIT_L(n) asm volatile("s_waitcnt lgkmcnt(" #n ")" ::: "memory")
; #define PG8_BAR __builtin_amdgcn_s_barrier()
; #define PG8_SCHED __builtin_amdgcn_sched_barrier(0)
; template <class Epi>
; __device__ __forceinline__ void gemm_phase(LAS unsigned char* lds, const Gemm g, const StaticOrder& S, const Epi& E) {
;     ...
;             PG8_STAGE(PG8_SB(0, 1), b2 + hstepB, voffB);
;             PG8_WAIT_V(6); PG8_BAR; PG8_MMA(1, 1, At, B1); PG8_BAR;
;             PG8_LDB(B0, 1, 0); PG8_SCHED; PG8_LDA(At, 1, 0); PG8_STAGE(PG8_SA(0, 1), a2 + hstepA, voffA);
;             PG8_WAIT_L(8); PG8_BAR; PG8_WAIT_L(0); PG8_MMA(0, 0, At, B0); PG8_BAR; PG8_SCHED;
;             PG8_LDB(B1, 1, 1); PG8_STAGE(PG8_SB(1, 0), b3, voffB);
;             PG8_BAR; PG8_WAIT_L(0); PG8_MMA(0, 1, At, B1); PG8_BAR;
;             PG8_LDA(At, 1, 1); PG8_STAGE(PG8_SA(1, 0), a3, voffA);
;             PG8_BAR; PG8_WAIT_L(0); PG8_MMA(1, 0, At, B0); PG8_BAR; PG8_SCHED;
	s_add_u32 s56, s24, 0x80000
	s_addc_u32 s57, s25, 0
	s_add_i32 s55, s58, s36
	s_mov_b32 m0, s55
	v_lshl_add_u64 v[136:137], s[56:57], 0, v[128:129]
	global_load_lds_dwordx4 v[136:137], off
	s_add_i32 m0, s55, 0x2000
	v_lshl_add_u64 v[136:137], s[56:57], 0, v[130:131]
	global_load_lds_dwordx4 v[136:137], off
	s_waitcnt vmcnt(6)
	s_barrier
	v_mfma_f32_16x16x32_bf16 v[52:55], v[188:191], v[156:159], v[52:55]
	s_setprio 1
	v_mfma_f32_16x16x32_bf16 v[48:51], v[196:199], v[156:159], v[48:51]
	s_add_i32 s55, 0, 0x18000
	v_add_u32_e32 v148, s55, v134
	v_mfma_f32_16x16x32_bf16 v[36:39], v[188:191], v[164:167], v[36:39]
	v_mfma_f32_16x16x32_bf16 v[32:35], v[196:199], v[164:167], v[32:35]
	v_mfma_f32_16x16x32_bf16 v[20:23], v[188:191], v[172:175], v[20:23]
	v_mfma_f32_16x16x32_bf16 v[16:19], v[196:199], v[172:175], v[16:19]
	v_mfma_f32_16x16x32_bf16 v[4:7], v[188:191], v[180:183], v[4:7]
	v_mfma_f32_16x16x32_bf16 v[0:3], v[196:199], v[180:183], v[0:3]
	v_mfma_f32_16x16x32_bf16 v[52:55], v[192:195], v[160:163], v[52:55]
	v_mfma_f32_16x16x32_bf16 v[48:51], v[200:203], v[160:163], v[48:51]
	v_mfma_f32_16x16x32_bf16 v[36:39], v[192:195], v[168:171], v[36:39]
	v_mfma_f32_16x16x32_bf16 v[32:35], v[200:203], v[168:171], v[32:35]
	v_mfma_f32_16x16x32_bf16 v[20:23], v[192:195], v[176:179], v[20:23]
	v_mfma_f32_16x16x32_bf16 v[16:19], v[200:203], v[176:179], v[16:19]
	v_mfma_f32_16x16x32_bf16 v[4:7], v[192:195], v[184:187], v[4:7]
	s_setprio 0
	v_mfma_f32_16x16x32_bf16 v[0:3], v[200:203], v[184:187], v[0:3]
	s_barrier
	ds_read_b128 v[136:139], v148
	ds_read_b128 v[140:143], v148 offset:1024
	ds_read_b128 v[144:147], v148 offset:2048
	ds_read_b128 v[148:151], v148 offset:3072
	ds_read_b128 v[156:159], v135 offset:32768
	ds_read_b128 v[160:163], v135 offset:33792
	ds_read_b128 v[164:167], v135 offset:34816
	ds_read_b128 v[168:171], v135 offset:35840
	ds_read_b128 v[172:175], v135 offset:36864
	ds_read_b128 v[176:179], v135 offset:37888
	ds_read_b128 v[180:183], v135 offset:38912
	ds_read_b128 v[184:187], v135 offset:39936
	s_add_u32 s28, s28, 0x80000
	s_addc_u32 s29, s29, 0
	s_mov_b32 m0, s39
	v_lshl_add_u64 v[188:189], s[28:29], 0, v[128:129]
	global_load_lds_dwordx4 v[188:189], off
	s_mov_b32 m0, s40
	v_lshl_add_u64 v[188:189], s[28:29], 0, v[130:131]
	global_load_lds_dwordx4 v[188:189], off
	s_waitcnt lgkmcnt(8)
	s_barrier
	s_waitcnt lgkmcnt(0)
	v_mfma_f32_16x16x32_bf16 v[124:127], v[136:139], v[156:159], v[124:127]
	s_setprio 1
	v_mfma_f32_16x16x32_bf16 v[120:123], v[144:147], v[156:159], v[120:123]
	v_mfma_f32_16x16x32_bf16 v[108:111], v[136:139], v[164:167], v[108:111]
	v_mfma_f32_16x16x32_bf16 v[104:107], v[144:147], v[164:167], v[104:107]
	v_mfma_f32_16x16x32_bf16 v[92:95], v[136:139], v[172:175], v[92:95]
	v_mfma_f32_16x16x32_bf16 v[88:91], v[144:147], v[172:175], v[88:91]
	v_mfma_f32_16x16x32_bf16 v[76:79], v[136:139], v[180:183], v[76:79]
	v_mfma_f32_16x16x32_bf16 v[72:75], v[144:147], v[180:183], v[72:75]
	v_mfma_f32_16x16x32_bf16 v[124:127], v[140:143], v[160:163], v[124:127]
	v_mfma_f32_16x16x32_bf16 v[120:123], v[148:151], v[160:163], v[120:123]
	v_mfma_f32_16x16x32_bf16 v[108:111], v[140:143], v[168:171], v[108:111]
	v_mfma_f32_16x16x32_bf16 v[104:107], v[148:151], v[168:171], v[104:107]
	v_mfma_f32_16x16x32_bf16 v[92:95], v[140:143], v[176:179], v[92:95]
	v_mfma_f32_16x16x32_bf16 v[88:91], v[148:151], v[176:179], v[88:91]
	v_mfma_f32_16x16x32_bf16 v[76:79], v[140:143], v[184:187], v[76:79]
	s_setprio 0
	v_mfma_f32_16x16x32_bf16 v[72:75], v[148:151], v[184:187], v[72:75]
	s_barrier
	s_mov_b32 s56, 0x1c000
	v_add_u32_e32 v152, s56, v134
	ds_read_b128 v[188:191], v152
	ds_read_b128 v[192:195], v152 offset:1024
	ds_read_b128 v[196:199], v152 offset:2048
	ds_read_b128 v[200:203], v152 offset:3072
	s_add_u32 s28, s24, 0x4000
	s_addc_u32 s29, s25, 0
	s_add_i32 s55, s55, s36
	s_mov_b32 m0, s55
	v_lshl_add_u64 v[204:205], s[28:29], 0, v[128:129]
	global_load_lds_dwordx4 v[204:205], off
	s_add_i32 m0, s55, 0x2000
	v_lshl_add_u64 v[204:205], s[28:29], 0, v[130:131]
	global_load_lds_dwordx4 v[204:205], off
	s_barrier
	s_waitcnt lgkmcnt(0)
	v_mfma_f32_16x16x32_bf16 v[116:119], v[188:191], v[156:159], v[116:119]
	s_setprio 1
	v_mfma_f32_16x16x32_bf16 v[112:115], v[196:199], v[156:159], v[112:115]
	s_mov_b32 m0, s43
	v_lshl_add_u64 v[204:205], s[26:27], 0, v[128:129]
	v_mfma_f32_16x16x32_bf16 v[100:103], v[188:191], v[164:167], v[100:103]
	v_mfma_f32_16x16x32_bf16 v[96:99], v[196:199], v[164:167], v[96:99]
	v_mfma_f32_16x16x32_bf16 v[84:87], v[188:191], v[172:175], v[84:87]
	v_mfma_f32_16x16x32_bf16 v[80:83], v[196:199], v[172:175], v[80:83]
	v_mfma_f32_16x16x32_bf16 v[68:71], v[188:191], v[180:183], v[68:71]
	v_mfma_f32_16x16x32_bf16 v[64:67], v[196:199], v[180:183], v[64:67]
	v_mfma_f32_16x16x32_bf16 v[116:119], v[192:195], v[160:163], v[116:119]
	v_mfma_f32_16x16x32_bf16 v[112:115], v[200:203], v[160:163], v[112:115]
	v_mfma_f32_16x16x32_bf16 v[100:103], v[192:195], v[168:171], v[100:103]
	v_mfma_f32_16x16x32_bf16 v[96:99], v[200:203], v[168:171], v[96:99]
	v_mfma_f32_16x16x32_bf16 v[84:87], v[192:195], v[176:179], v[84:87]
	v_mfma_f32_16x16x32_bf16 v[80:83], v[200:203], v[176:179], v[80:83]
	v_mfma_f32_16x16x32_bf16 v[68:71], v[192:195], v[184:187], v[68:71]
	s_setprio 0
	v_mfma_f32_16x16x32_bf16 v[64:67], v[200:203], v[184:187], v[64:67]
	s_barrier
	ds_read_b128 v[156:159], v135 offset:49152
	ds_read_b128 v[160:163], v135 offset:50176
	ds_read_b128 v[164:167], v135 offset:51200
	ds_read_b128 v[168:171], v135 offset:52224
	ds_read_b128 v[172:175], v135 offset:53248
	ds_read_b128 v[176:179], v135 offset:54272
	ds_read_b128 v[180:183], v135 offset:55296
	ds_read_b128 v[184:187], v135 offset:56320
	global_load_lds_dwordx4 v[204:205], off
	s_mov_b32 m0, s44
	v_lshl_add_u64 v[204:205], s[26:27], 0, v[130:131]
	global_load_lds_dwordx4 v[204:205], off
	s_barrier
; __device__ __forceinline__ unsigned cvt_pk_bf16(float lo, float hi) { unsigned r; asm volatile("v_cvt_pk_bf16_f32 %0, %1, %2" : "=v"(r) : "v"(lo), "v"(hi)); return r; }
; #define PG8_STAGE(bufoff, gbase, voff) do { _Pragma("unroll") for (int _i = 0; _i < 2; ++_i) \
;         __builtin_amdgcn_global_load_lds((const unsigned*)((const char*)(gbase) + (voff)[_i]), (LAS unsigned*)(lds + (bufoff) + ldsw + _i * 8192), 16, 0, 0); } while (0)
; #define PG8_MMA(ai, bj, At, Bt) do { __builtin_amdgcn_s_setprio(1); _Pragma("unroll") for (int m = 0; m < 4; ++m) _Pragma("unroll") for (int n = 0; n < 2; ++n) _Pragma("unroll") for (int k = 0; k < 2; ++k) \
;         acc[ai][bj][m][n] = __builtin_amdgcn_mfma_f32_16x16x32_bf16(Bt[n][k], At[m][k], acc[ai][bj][m][n], 0, 0, 0); __builtin_amdgcn_s_setprio(0); } while (0)
; #define PG8_WAIT_V(n) asm volatile("s_waitcnt vmcnt(" #n ")" ::: "memory")
; #define PG8_WAIT_L(n) asm volatile("s_waitcnt lgkmcnt(" #n ")" ::: "memory")
; #define PG8_BAR __builtin_amdgcn_s_barrier()
; #define PG8_SCHED __builtin_amdgcn_sched_barrier(0)
; template <class Epi>
; __device__ __forceinline__ void gemm_phase(LAS unsigned char* lds, const Gemm g, const StaticOrder& S, const Epi& E) {
;     ...
;             PG8_BAR; PG8_WAIT_L(0); PG8_MMA(1, 0, At, B0); PG8_BAR; PG8_SCHED;
;             PG8_STAGE(PG8_SB(1, 1), b3 + hstepB, voffB);
;             PG8_WAIT_V(6); PG8_BAR; PG8_MMA(1, 1, At, B1); PG8_BAR;
;     __device__ __forceinline__ void operator()(const f32x4 (&acc)[2][2][4][2], const Unit& u, int wr, int wc, int fr, int fq) const {
;         const int row0 = u.pm * BM + wr * 64 + fr, col0 = u.pn * BM + wc * 32 + 8 * fq;
; #pragma unroll
;         for (int ai = 0; ai < 2; ++ai)
; #pragma unroll
;             for (int m = 0; m < 4; ++m) {
;                 const int rowi = row0 + ai * HALF + m * 16;
; #pragma unroll
;                 for (int bj = 0; bj < 2; ++bj) {
;                     f32x4 v0 = acc[ai][bj][m][0], v1 = acc[ai][bj][m][1];
; #pragma unroll
;                     for (int j = 0; j < 4; ++j) { const float a = fmaxf(v0[j], 0.f), b = fmaxf(v1[j], 0.f); v0[j] = a * a; v1[j] = b * b; }
;                     u32x4 w; w.x = cvt_pk_bf16(v0[0], v0[1]); w.y = cvt_pk_bf16(v0[2], v0[3]); w.z = cvt_pk_bf16(v1[0], v1[1]); w.w = cvt_pk_bf16(v1[2], v1[3]);
;                     *(u32x4*)(O + tiled_off(rowi, col0 + bj * HALF, DFF / 64)) = w;
	s_waitcnt lgkmcnt(0)
	v_mfma_f32_16x16x32_bf16 v[60:63], v[136:139], v[156:159], v[60:63]
	s_setprio 1
	v_mfma_f32_16x16x32_bf16 v[56:59], v[144:147], v[156:159], v[56:59]
	v_mfma_f32_16x16x32_bf16 v[44:47], v[136:139], v[164:167], v[44:47]
	v_mfma_f32_16x16x32_bf16 v[40:43], v[144:147], v[164:167], v[40:43]
	v_mfma_f32_16x16x32_bf16 v[28:31], v[136:139], v[172:175], v[28:31]
	v_mfma_f32_16x16x32_bf16 v[24:27], v[144:147], v[172:175], v[24:27]
	v_mfma_f32_16x16x32_bf16 v[12:15], v[136:139], v[180:183], v[12:15]
	v_mfma_f32_16x16x32_bf16 v[8:11], v[144:147], v[180:183], v[8:11]
	v_mfma_f32_16x16x32_bf16 v[60:63], v[140:143], v[160:163], v[60:63]
	v_mfma_f32_16x16x32_bf16 v[56:59], v[148:151], v[160:163], v[56:59]
	v_mfma_f32_16x16x32_bf16 v[44:47], v[140:143], v[168:171], v[44:47]
	v_mfma_f32_16x16x32_bf16 v[40:43], v[148:151], v[168:171], v[40:43]
	v_mfma_f32_16x16x32_bf16 v[28:31], v[140:143], v[176:179], v[28:31]
	v_mfma_f32_16x16x32_bf16 v[24:27], v[148:151], v[176:179], v[24:27]
	v_mfma_f32_16x16x32_bf16 v[12:15], v[140:143], v[184:187], v[12:15]
	s_setprio 0
	v_mfma_f32_16x16x32_bf16 v[8:11], v[148:151], v[184:187], v[8:11]
	s_barrier
	s_add_u32 s24, s24, 0x84000
	s_addc_u32 s25, s25, 0
	s_add_i32 s26, s56, s36
	s_mov_b32 m0, s26
	v_lshl_add_u64 v[136:137], s[24:25], 0, v[128:129]
	global_load_lds_dwordx4 v[136:137], off
	s_add_i32 m0, s26, 0x2000
	v_lshl_add_u64 v[136:137], s[24:25], 0, v[130:131]
	global_load_lds_dwordx4 v[136:137], off
	s_waitcnt vmcnt(6)
	s_barrier
	v_mfma_f32_16x16x32_bf16 v[52:55], v[188:191], v[156:159], v[52:55]
	s_setprio 1
	v_mfma_f32_16x16x32_bf16 v[48:51], v[196:199], v[156:159], v[48:51]
	s_add_i32 s54, s54, 2
	s_add_u32 s22, s22, 0x8000
	s_addc_u32 s23, s23, 0
	s_add_u32 s51, s51, 0x8000
	s_addc_u32 s52, s52, 0
	v_mfma_f32_16x16x32_bf16 v[36:39], v[188:191], v[164:167], v[36:39]
	v_mfma_f32_16x16x32_bf16 v[32:35], v[196:199], v[164:167], v[32:35]
	v_mfma_f32_16x16x32_bf16 v[20:23], v[188:191], v[172:175], v[20:23]
	v_mfma_f32_16x16x32_bf16 v[16:19], v[196:199], v[172:175], v[16:19]
	v_mfma_f32_16x16x32_bf16 v[4:7], v[188:191], v[180:183], v[4:7]
	v_mfma_f32_16x16x32_bf16 v[0:3], v[196:199], v[180:183], v[0:3]
	v_mfma_f32_16x16x32_bf16 v[52:55], v[192:195], v[160:163], v[52:55]
	v_mfma_f32_16x16x32_bf16 v[48:51], v[200:203], v[160:163], v[48:51]
	v_mfma_f32_16x16x32_bf16 v[36:39], v[192:195], v[168:171], v[36:39]
	v_mfma_f32_16x16x32_bf16 v[32:35], v[200:203], v[168:171], v[32:35]
	v_mfma_f32_16x16x32_bf16 v[20:23], v[192:195], v[176:179], v[20:23]
	v_mfma_f32_16x16x32_bf16 v[16:19], v[200:203], v[176:179], v[16:19]
	v_mfma_f32_16x16x32_bf16 v[4:7], v[192:195], v[184:187], v[4:7]
	s_cmp_gt_u32 s54, 29
	s_setprio 0
	v_mfma_f32_16x16x32_bf16 v[0:3], v[200:203], v[184:187], v[0:3]
	s_barrier
	s_cbranch_scc0 .LBB0_141
	s_lshl_b32 s24, s20, 8
	s_lshl_b32 s5, s21, 8
	s_add_i32 s24, s24, s41
	s_or_b32 s5, s5, s42
	s_and_b32 s22, s24, 0xffffff80
	s_ashr_i32 s5, s5, 6
	s_add_i32 s20, s22, s5
	s_ashr_i32 s21, s20, 31
	v_max_f32_e32 v120, 0, v120
	s_lshl_b64 s[20:21], s[20:21], 14
	v_readlane_b32 s26, v252, 57
	v_or_b32_e32 v136, s24, v132
	v_mul_f32_e32 v140, v120, v120
	v_max_f32_e32 v121, 0, v121
	v_max_f32_e32 v122, 0, v122
	v_readlane_b32 s27, v252, 58
	s_add_u32 s20, s26, s20
	v_lshlrev_b32_e32 v137, 6, v136
	s_movk_i32 s28, 0x3c0
	v_lshlrev_b32_e32 v138, 2, v136
	v_max_f32_e32 v120, 0, v125
	v_mul_f32_e32 v125, v121, v121
	v_max_f32_e32 v121, v126, v126
	v_mul_f32_e32 v126, v122, v122
	s_addc_u32 s21, s27, s21
	s_or_b32 s15, s5, 2
	v_and_or_b32 v137, v137, s28, v133
	v_and_b32_e32 v138, 32, v138
	v_max_f32_e32 v124, 0, v124
	v_mul_f32_e32 v120, v120, v120
	v_max_f32_e32 v121, 0, v121
	v_max_f32_e32 v122, 0, v127
	v_max_f32_e32 v123, 0, v123
	s_add_i32 s22, s15, s22
	v_bitop3_b32 v139, v137, s46, v138 bitop3:0xde
	v_mul_f32_e32 v124, v124, v124
	v_mul_f32_e32 v121, v121, v121
	v_mul_f32_e32 v122, v122, v122
	v_mul_f32_e32 v123, v123, v123
	v_cvt_pk_bf16_f32 v120, v124, v120
	v_max_f32_e32 v112, 0, v112
	v_max_f32_e32 v113, 0, v113
	s_ashr_i32 s23, s22, 31
	v_cvt_pk_bf16_f32 v121, v121, v122
	v_cvt_pk_bf16_f32 v122, v140, v125
	v_cvt_pk_bf16_f32 v123, v126, v123
	global_store_dwordx4 v139, v[120:123], s[20:21]
	v_max_f32_e32 v114, 0, v114
	s_lshl_b64 s[22:23], s[22:23], 14
	v_mul_f32_e32 v120, v112, v112
	v_max_f32_e32 v112, v117, v117
	v_mul_f32_e32 v117, v113, v113
	v_max_f32_e32 v112, 0, v112
	v_max_f32_e32 v113, 0, v118
	v_mul_f32_e32 v118, v114, v114
	s_add_u32 s22, s26, s22
	v_max_f32_e32 v116, 0, v116
	v_mul_f32_e32 v112, v112, v112
	v_mul_f32_e32 v113, v113, v113
	v_max_f32_e32 v114, 0, v119
	v_max_f32_e32 v115, 0, v115
	s_addc_u32 s23, s27, s23
	s_or_b32 s25, s24, 16
	v_mul_f32_e32 v116, v116, v116
	v_mul_f32_e32 v114, v114, v114
	v_mul_f32_e32 v115, v115, v115
	v_cvt_pk_bf16_f32 v112, v116, v112
	v_cvt_pk_bf16_f32 v113, v113, v114
	s_lshr_b32 s25, s25, 3
	v_max_f32_e32 v104, 0, v104
	v_cvt_pk_bf16_f32 v114, v120, v117
	v_cvt_pk_bf16_f32 v115, v118, v115
	global_store_dwordx4 v139, v[112:115], s[22:23]
	s_and_b32 s25, s25, 10
	v_max_f32_e32 v105, 0, v105
	v_mul_f32_e32 v113, v104, v104
	v_max_f32_e32 v106, 0, v106
	s_or_b32 s25, s25, s45
	v_max_f32_e32 v104, 0, v109
	v_mul_f32_e32 v109, v105, v105
	v_max_f32_e32 v105, v110, v110
	v_mul_f32_e32 v110, v106, v106
	s_lshl_b32 s25, s25, 10
	v_max_f32_e32 v108, 0, v108
	v_mul_f32_e32 v104, v104, v104
	v_max_f32_e32 v105, 0, v105
	v_max_f32_e32 v106, 0, v111
	v_max_f32_e32 v107, 0, v107
	v_bitop3_b32 v112, v137, s25, v138 bitop3:0xde
	v_mul_f32_e32 v108, v108, v108
	v_mul_f32_e32 v105, v105, v105
	v_mul_f32_e32 v106, v106, v106
	v_mul_f32_e32 v107, v107, v107
; __device__ __forceinline__ unsigned cvt_pk_bf16(float lo, float hi) { unsigned r; asm volatile("v_cvt_pk_bf16_f32 %0, %1, %2" : "=v"(r) : "v"(lo), "v"(hi)); return r; }
;     __device__ __forceinline__ void operator()(const f32x4 (&acc)[2][2][4][2], const Unit& u, int wr, int wc, int fr, int fq) const {
;     ...
;         for (int ai = 0; ai < 2; ++ai)
; #pragma unroll
;             for (int m = 0; m < 4; ++m) {
;                 const int rowi = row0 + ai * HALF + m * 16;
; #pragma unroll
;                 for (int bj = 0; bj < 2; ++bj) {
;                     f32x4 v0 = acc[ai][bj][m][0], v1 = acc[ai][bj][m][1];
; #pragma unroll
;                     for (int j = 0; j < 4; ++j) { const float a = fmaxf(v0[j], 0.f), b = fmaxf(v1[j], 0.f); v0[j] = a * a; v1[j] = b * b; }
;                     u32x4 w; w.x = cvt_pk_bf16(v0[0], v0[1]); w.y = cvt_pk_bf16(v0[2], v0[3]); w.z = cvt_pk_bf16(v1[0], v1[1]); w.w = cvt_pk_bf16(v1[2], v1[3]);
;                     *(u32x4*)(O + tiled_off(rowi, col0 + bj * HALF, DFF / 64)) = w;
;                 }
	v_cvt_pk_bf16_f32 v104, v108, v104
	v_max_f32_e32 v96, 0, v96
	v_max_f32_e32 v97, 0, v97
	v_cvt_pk_bf16_f32 v105, v105, v106
	v_cvt_pk_bf16_f32 v106, v113, v109
	v_cvt_pk_bf16_f32 v107, v110, v107
	global_store_dwordx4 v112, v[104:107], s[20:21]
	s_nop 0
	v_max_f32_e32 v98, 0, v98
	v_mul_f32_e32 v104, v96, v96
	v_max_f32_e32 v96, v101, v101
	v_mul_f32_e32 v101, v97, v97
	v_max_f32_e32 v96, 0, v96
	v_max_f32_e32 v97, 0, v102
	v_mul_f32_e32 v102, v98, v98
	v_max_f32_e32 v100, 0, v100
	v_mul_f32_e32 v96, v96, v96
	v_mul_f32_e32 v97, v97, v97
	v_max_f32_e32 v98, 0, v103
	v_max_f32_e32 v99, 0, v99
	s_or_b32 s25, s24, 32
	v_mul_f32_e32 v100, v100, v100
	v_mul_f32_e32 v98, v98, v98
	v_mul_f32_e32 v99, v99, v99
	v_cvt_pk_bf16_f32 v96, v100, v96
	v_cvt_pk_bf16_f32 v97, v97, v98
	s_lshr_b32 s25, s25, 3
	v_max_f32_e32 v88, 0, v88
	v_cvt_pk_bf16_f32 v98, v104, v101
	v_cvt_pk_bf16_f32 v99, v102, v99
	global_store_dwordx4 v112, v[96:99], s[22:23]
	s_and_b32 s25, s25, 12
	v_max_f32_e32 v89, 0, v89
	v_mul_f32_e32 v97, v88, v88
	v_max_f32_e32 v90, 0, v90
	s_or_b32 s25, s25, s45
	v_max_f32_e32 v88, 0, v93
	v_mul_f32_e32 v93, v89, v89
	v_max_f32_e32 v89, v94, v94
	v_mul_f32_e32 v94, v90, v90
	s_lshl_b32 s25, s25, 10
	v_max_f32_e32 v92, 0, v92
	v_mul_f32_e32 v88, v88, v88
	v_max_f32_e32 v89, 0, v89
	v_max_f32_e32 v90, 0, v95
	v_max_f32_e32 v91, 0, v91
	v_bitop3_b32 v96, v137, s25, v138 bitop3:0xde
	v_mul_f32_e32 v92, v92, v92
	v_mul_f32_e32 v89, v89, v89
	v_mul_f32_e32 v90, v90, v90
	v_mul_f32_e32 v91, v91, v91
	v_cvt_pk_bf16_f32 v88, v92, v88
	v_max_f32_e32 v80, 0, v80
	v_max_f32_e32 v81, 0, v81
	v_cvt_pk_bf16_f32 v89, v89, v90
	v_cvt_pk_bf16_f32 v90, v97, v93
	v_cvt_pk_bf16_f32 v91, v94, v91
	global_store_dwordx4 v96, v[88:91], s[20:21]
	s_nop 0
	v_max_f32_e32 v82, 0, v82
	v_mul_f32_e32 v88, v80, v80
	v_max_f32_e32 v80, v85, v85
	v_mul_f32_e32 v85, v81, v81
	v_max_f32_e32 v80, 0, v80
	v_max_f32_e32 v81, 0, v86
	v_mul_f32_e32 v86, v82, v82
	v_max_f32_e32 v84, 0, v84
	v_mul_f32_e32 v80, v80, v80
	v_mul_f32_e32 v81, v81, v81
	v_max_f32_e32 v82, 0, v87
	v_max_f32_e32 v83, 0, v83
	s_or_b32 s24, s24, 48
	v_mul_f32_e32 v84, v84, v84
	v_mul_f32_e32 v82, v82, v82
	v_mul_f32_e32 v83, v83, v83
	v_cvt_pk_bf16_f32 v80, v84, v80
	v_cvt_pk_bf16_f32 v81, v81, v82
	s_lshr_b32 s24, s24, 3
	v_max_f32_e32 v72, 0, v72
	v_cvt_pk_bf16_f32 v82, v88, v85
	v_cvt_pk_bf16_f32 v83, v86, v83
	global_store_dwordx4 v96, v[80:83], s[22:23]
	s_and_b32 s24, s24, 14
	v_max_f32_e32 v73, 0, v73
	v_mul_f32_e32 v81, v72, v72
	v_max_f32_e32 v74, 0, v74
	s_or_b32 s24, s24, s45
	v_max_f32_e32 v72, 0, v77
	v_mul_f32_e32 v77, v73, v73
	v_max_f32_e32 v73, v78, v78
	v_mul_f32_e32 v78, v74, v74
	s_lshl_b32 s24, s24, 10
	v_max_f32_e32 v76, 0, v76
	v_mul_f32_e32 v72, v72, v72
	v_max_f32_e32 v73, 0, v73
	v_max_f32_e32 v74, 0, v79
	v_max_f32_e32 v75, 0, v75
	v_bitop3_b32 v80, v137, s24, v138 bitop3:0xde
	v_mul_f32_e32 v76, v76, v76
	v_mul_f32_e32 v73, v73, v73
	v_mul_f32_e32 v74, v74, v74
	v_mul_f32_e32 v75, v75, v75
	v_cvt_pk_bf16_f32 v72, v76, v72
	v_max_f32_e32 v64, 0, v64
	v_cvt_pk_bf16_f32 v73, v73, v74
	v_cvt_pk_bf16_f32 v74, v81, v77
	v_cvt_pk_bf16_f32 v75, v78, v75
	global_store_dwordx4 v80, v[72:75], s[20:21]
	v_max_f32_e32 v65, 0, v65
	v_max_f32_e32 v66, 0, v66
	v_mul_f32_e32 v72, v64, v64
	v_max_f32_e32 v64, 0, v69
	v_mul_f32_e32 v69, v65, v65
	v_max_f32_e32 v65, v70, v70
	v_mul_f32_e32 v70, v66, v66
	v_max_f32_e32 v68, 0, v68
	v_mul_f32_e32 v64, v64, v64
	v_max_f32_e32 v65, 0, v65
	v_max_f32_e32 v66, 0, v71
	v_max_f32_e32 v67, 0, v67
	v_mul_f32_e32 v68, v68, v68
	v_mul_f32_e32 v65, v65, v65
	v_mul_f32_e32 v66, v66, v66
	v_mul_f32_e32 v67, v67, v67
	v_cvt_pk_bf16_f32 v64, v68, v64
	v_cvt_pk_bf16_f32 v65, v65, v66
	v_cvt_pk_bf16_f32 v66, v72, v69
	v_cvt_pk_bf16_f32 v67, v70, v67
	global_store_dwordx4 v80, v[64:67], s[22:23]
	s_nop 0
	v_max_f32_e32 v56, 0, v56
	v_add_u32_e32 v64, 0x80, v136
	v_and_b32_e32 v65, 0xffffff80, v64
	v_lshlrev_b32_e32 v66, 6, v64
	v_lshlrev_b32_e32 v64, 2, v64
	v_and_or_b32 v66, v66, s28, v133
	v_and_b32_e32 v64, 32, v64
	v_bitop3_b32 v152, v66, s46, v64 bitop3:0xde
	v_mul_f32_e32 v64, v56, v56
	v_max_f32_e32 v57, 0, v57
	v_max_f32_e32 v58, 0, v58
	v_max_f32_e32 v60, 0, v60
	v_max_f32_e32 v56, 0, v61
	v_mul_f32_e32 v61, v57, v57
	v_max_f32_e32 v57, v62, v62
	v_mul_f32_e32 v62, v58, v58
	v_mul_f32_e32 v60, v60, v60
	v_mul_f32_e32 v56, v56, v56
	v_max_f32_e32 v57, 0, v57
	v_max_f32_e32 v58, 0, v63
	v_mul_f32_e32 v57, v57, v57
	v_mul_f32_e32 v58, v58, v58
	v_cvt_pk_bf16_f32 v56, v60, v56
	v_add_u32_e32 v60, s5, v65
	v_cvt_pk_bf16_f32 v57, v57, v58
	v_cvt_pk_bf16_f32 v58, v64, v61
	v_ashrrev_i32_e32 v61, 31, v60
	v_max_f32_e32 v59, 0, v59
	v_lshlrev_b64 v[60:61], 14, v[60:61]
	v_mul_f32_e32 v59, v59, v59
	v_lshl_add_u64 v[60:61], s[26:27], 0, v[60:61]
	v_cvt_pk_bf16_f32 v59, v62, v59
	v_lshl_add_u64 v[62:63], v[60:61], 0, v[152:153]
	v_max_f32_e32 v48, 0, v48
	global_store_dwordx4 v[62:63], v[56:59], off
	s_nop 0
	v_max_f32_e32 v49, 0, v49
	v_mul_f32_e32 v56, v48, v48
	v_max_f32_e32 v50, 0, v50
	v_max_f32_e32 v52, 0, v52
	v_max_f32_e32 v48, 0, v53
	v_mul_f32_e32 v53, v49, v49
	v_max_f32_e32 v49, v54, v54
	v_mul_f32_e32 v54, v50, v50
	v_mul_f32_e32 v52, v52, v52
	v_mul_f32_e32 v48, v48, v48
	v_max_f32_e32 v49, 0, v49
	v_max_f32_e32 v50, 0, v55
	v_mul_f32_e32 v49, v49, v49
	v_mul_f32_e32 v50, v50, v50
	v_cvt_pk_bf16_f32 v48, v52, v48
	v_add_u32_e32 v52, s15, v65
	v_cvt_pk_bf16_f32 v49, v49, v50
	v_cvt_pk_bf16_f32 v50, v56, v53
	v_ashrrev_i32_e32 v53, 31, v52
	v_max_f32_e32 v51, 0, v51
	v_lshlrev_b64 v[52:53], 14, v[52:53]
	v_mul_f32_e32 v51, v51, v51
; __device__ __forceinline__ unsigned cvt_pk_bf16(float lo, float hi) { unsigned r; asm volatile("v_cvt_pk_bf16_f32 %0, %1, %2" : "=v"(r) : "v"(lo), "v"(hi)); return r; }
; template <class Epi>
; __device__ __forceinline__ void gemm_phase(LAS unsigned char* lds, const Gemm g, const StaticOrder& S, const Epi& E) {
;     ...
;         E(acc, cur, wr, wc, fr, fq);
;         if (!has_next) break;
; #pragma unroll
;         for (int a = 0; a < 2; ++a)
; #pragma unroll
;             for (int b = 0; b < 2; ++b)
; #pragma unroll
;                 for (int m = 0; m < 4; ++m)
; #pragma unroll
;                     for (int n = 0; n < 2; ++n) acc[a][b][m][n] = (f32x4){0.f, 0.f, 0.f, 0.f};
;         cur = nxt; cA = nA; cB = nB; ++ui;
;     __device__ __forceinline__ void operator()(const f32x4 (&acc)[2][2][4][2], const Unit& u, int wr, int wc, int fr, int fq) const {
;     ...
;         for (int ai = 0; ai < 2; ++ai)
; #pragma unroll
;             for (int m = 0; m < 4; ++m) {
;                 const int rowi = row0 + ai * HALF + m * 16;
; #pragma unroll
;                 for (int bj = 0; bj < 2; ++bj) {
;                     f32x4 v0 = acc[ai][bj][m][0], v1 = acc[ai][bj][m][1];
; #pragma unroll
;                     for (int j = 0; j < 4; ++j) { const float a = fmaxf(v0[j], 0.f), b = fmaxf(v1[j], 0.f); v0[j] = a * a; v1[j] = b * b; }
;                     u32x4 w; w.x = cvt_pk_bf16(v0[0], v0[1]); w.y = cvt_pk_bf16(v0[2], v0[3]); w.z = cvt_pk_bf16(v1[0], v1[1]); w.w = cvt_pk_bf16(v1[2], v1[3]);
;                     *(u32x4*)(O + tiled_off(rowi, col0 + bj * HALF, DFF / 64)) = w;
;                 }
	v_lshl_add_u64 v[52:53], s[26:27], 0, v[52:53]
	v_cvt_pk_bf16_f32 v51, v54, v51
	v_lshl_add_u64 v[54:55], v[52:53], 0, v[152:153]
	global_store_dwordx4 v[54:55], v[48:51], off
	s_nop 1
	v_add_u32_e32 v48, 0x90, v136
	v_lshrrev_b32_e32 v49, 3, v48
	v_and_or_b32 v49, v49, 10, s45
	v_lshlrev_b32_e32 v50, 6, v48
	v_lshlrev_b32_e32 v48, 2, v48
	v_and_or_b32 v50, v50, s28, v133
	v_lshlrev_b32_e32 v49, 10, v49
	v_and_b32_e32 v48, 32, v48
	v_max_f32_e32 v40, 0, v40
	v_max_f32_e32 v41, 0, v41
	v_max_f32_e32 v42, 0, v42
	v_bitop3_b32 v152, v50, v49, v48 bitop3:0xde
	v_mul_f32_e32 v48, v40, v40
	v_max_f32_e32 v40, v45, v45
	v_mul_f32_e32 v45, v41, v41
	v_max_f32_e32 v41, v46, v46
	v_mul_f32_e32 v46, v42, v42
	v_max_f32_e32 v44, 0, v44
	v_max_f32_e32 v40, 0, v40
	v_max_f32_e32 v41, 0, v41
	v_max_f32_e32 v42, 0, v47
	v_mul_f32_e32 v44, v44, v44
	v_mul_f32_e32 v40, v40, v40
	v_mul_f32_e32 v41, v41, v41
	v_max_f32_e32 v43, 0, v43
	v_mul_f32_e32 v42, v42, v42
	v_mul_f32_e32 v43, v43, v43
	v_cvt_pk_bf16_f32 v40, v44, v40
	v_cvt_pk_bf16_f32 v41, v41, v42
	v_cvt_pk_bf16_f32 v42, v48, v45
	v_lshl_add_u64 v[44:45], v[60:61], 0, v[152:153]
	v_max_f32_e32 v32, 0, v32
	v_max_f32_e32 v33, 0, v33
	v_max_f32_e32 v34, 0, v34
	v_cvt_pk_bf16_f32 v43, v46, v43
	global_store_dwordx4 v[44:45], v[40:43], off
	s_nop 0
	v_max_f32_e32 v36, 0, v36
	v_mul_f32_e32 v40, v32, v32
	v_max_f32_e32 v32, v37, v37
	v_mul_f32_e32 v37, v33, v33
	v_max_f32_e32 v33, v38, v38
	v_mul_f32_e32 v38, v34, v34
	v_max_f32_e32 v32, 0, v32
	v_max_f32_e32 v33, 0, v33
	v_max_f32_e32 v34, 0, v39
	v_mul_f32_e32 v36, v36, v36
	v_mul_f32_e32 v32, v32, v32
	v_mul_f32_e32 v33, v33, v33
	v_max_f32_e32 v35, 0, v35
	v_mul_f32_e32 v34, v34, v34
	v_mul_f32_e32 v35, v35, v35
	v_cvt_pk_bf16_f32 v32, v36, v32
	v_cvt_pk_bf16_f32 v33, v33, v34
	v_cvt_pk_bf16_f32 v34, v40, v37
	v_lshl_add_u64 v[36:37], v[52:53], 0, v[152:153]
	v_cvt_pk_bf16_f32 v35, v38, v35
	global_store_dwordx4 v[36:37], v[32:35], off
	s_nop 1
	v_add_u32_e32 v32, 0xa0, v136
	v_lshrrev_b32_e32 v33, 3, v32
	v_and_or_b32 v33, v33, 12, s45
	v_lshlrev_b32_e32 v34, 6, v32
	v_lshlrev_b32_e32 v32, 2, v32
	v_and_or_b32 v34, v34, s28, v133
	v_lshlrev_b32_e32 v33, 10, v33
	v_and_b32_e32 v32, 32, v32
	v_max_f32_e32 v24, 0, v24
	v_max_f32_e32 v25, 0, v25
	v_max_f32_e32 v26, 0, v26
	v_bitop3_b32 v152, v34, v33, v32 bitop3:0xde
	v_mul_f32_e32 v32, v24, v24
	v_max_f32_e32 v24, v29, v29
	v_mul_f32_e32 v29, v25, v25
	v_max_f32_e32 v25, v30, v30
	v_mul_f32_e32 v30, v26, v26
	v_max_f32_e32 v28, 0, v28
	v_max_f32_e32 v24, 0, v24
	v_max_f32_e32 v25, 0, v25
	v_max_f32_e32 v26, 0, v31
	v_mul_f32_e32 v28, v28, v28
	v_mul_f32_e32 v24, v24, v24
	v_mul_f32_e32 v25, v25, v25
	v_max_f32_e32 v27, 0, v27
	v_mul_f32_e32 v26, v26, v26
	v_mul_f32_e32 v27, v27, v27
	v_cvt_pk_bf16_f32 v24, v28, v24
	v_cvt_pk_bf16_f32 v25, v25, v26
	v_cvt_pk_bf16_f32 v26, v32, v29
	v_lshl_add_u64 v[28:29], v[60:61], 0, v[152:153]
	v_max_f32_e32 v16, 0, v16
	v_max_f32_e32 v17, 0, v17
	v_max_f32_e32 v18, 0, v18
	v_cvt_pk_bf16_f32 v27, v30, v27
	global_store_dwordx4 v[28:29], v[24:27], off
	s_nop 0
	v_max_f32_e32 v20, 0, v20
	v_mul_f32_e32 v24, v16, v16
	v_max_f32_e32 v16, v21, v21
	v_mul_f32_e32 v21, v17, v17
	v_max_f32_e32 v17, v22, v22
	v_mul_f32_e32 v22, v18, v18
	v_max_f32_e32 v16, 0, v16
	v_max_f32_e32 v17, 0, v17
	v_max_f32_e32 v18, 0, v23
	v_mul_f32_e32 v20, v20, v20
	v_mul_f32_e32 v16, v16, v16
	v_mul_f32_e32 v17, v17, v17
	v_max_f32_e32 v19, 0, v19
	v_mul_f32_e32 v18, v18, v18
	v_mul_f32_e32 v19, v19, v19
	v_cvt_pk_bf16_f32 v16, v20, v16
	v_cvt_pk_bf16_f32 v17, v17, v18
	v_cvt_pk_bf16_f32 v18, v24, v21
	v_lshl_add_u64 v[20:21], v[52:53], 0, v[152:153]
	v_cvt_pk_bf16_f32 v19, v22, v19
	global_store_dwordx4 v[20:21], v[16:19], off
	s_nop 1
	v_add_u32_e32 v16, 0xb0, v136
	v_lshrrev_b32_e32 v17, 3, v16
	v_and_or_b32 v17, v17, 14, s45
	v_lshlrev_b32_e32 v18, 6, v16
	v_lshlrev_b32_e32 v16, 2, v16
	v_and_or_b32 v18, v18, s28, v133
	v_lshlrev_b32_e32 v17, 10, v17
	v_and_b32_e32 v16, 32, v16
	v_max_f32_e32 v8, 0, v8
	v_max_f32_e32 v9, 0, v9
	v_max_f32_e32 v10, 0, v10
	v_bitop3_b32 v152, v18, v17, v16 bitop3:0xde
	v_mul_f32_e32 v16, v8, v8
	v_max_f32_e32 v8, v13, v13
	v_mul_f32_e32 v13, v9, v9
	v_max_f32_e32 v9, v14, v14
	v_mul_f32_e32 v14, v10, v10
	v_max_f32_e32 v12, 0, v12
	v_max_f32_e32 v8, 0, v8
	v_max_f32_e32 v9, 0, v9
	v_max_f32_e32 v10, 0, v15
	v_mul_f32_e32 v12, v12, v12
	v_mul_f32_e32 v8, v8, v8
	v_mul_f32_e32 v9, v9, v9
	v_max_f32_e32 v11, 0, v11
	v_mul_f32_e32 v10, v10, v10
	v_mul_f32_e32 v11, v11, v11
	v_cvt_pk_bf16_f32 v8, v12, v8
	v_cvt_pk_bf16_f32 v9, v9, v10
	v_cvt_pk_bf16_f32 v10, v16, v13
	v_lshl_add_u64 v[12:13], v[60:61], 0, v[152:153]
	v_max_f32_e32 v0, 0, v0
	v_max_f32_e32 v1, 0, v1
	v_max_f32_e32 v2, 0, v2
	v_cvt_pk_bf16_f32 v11, v14, v11
	global_store_dwordx4 v[12:13], v[8:11], off
	s_nop 0
	v_max_f32_e32 v4, 0, v4
	v_mul_f32_e32 v8, v0, v0
	v_max_f32_e32 v0, v5, v5
	v_mul_f32_e32 v5, v1, v1
	v_max_f32_e32 v1, v6, v6
	v_mul_f32_e32 v6, v2, v2
	v_max_f32_e32 v0, 0, v0
	v_max_f32_e32 v1, 0, v1
	v_max_f32_e32 v2, 0, v7
	v_mul_f32_e32 v4, v4, v4
	v_mul_f32_e32 v0, v0, v0
	v_mul_f32_e32 v1, v1, v1
	v_max_f32_e32 v3, 0, v3
	v_mul_f32_e32 v2, v2, v2
	s_mov_b32 s54, 0xd00ab22c
	v_mul_f32_e32 v3, v3, v3
	v_cvt_pk_bf16_f32 v0, v4, v0
	v_cvt_pk_bf16_f32 v1, v1, v2
	v_cvt_pk_bf16_f32 v2, v8, v5
	v_lshl_add_u64 v[4:5], v[52:53], 0, v[152:153]
	s_and_b64 vcc, exec, s[0:1]
	s_mov_b32 s21, s4
	s_mov_b32 s20, s14
	s_mov_b64 s[24:25], s[18:19]
	s_mov_b64 s[22:23], s[16:17]
	s_mov_b32 s55, 0x3febb5fa
	v_cvt_pk_bf16_f32 v3, v6, v3
	global_store_dwordx4 v[4:5], v[0:3], off
	s_cbranch_vccz .LBB0_134
	s_waitcnt vmcnt(0)
	s_cmpk_gt_u32 s31, 0xff
	s_cbranch_scc1 .LBB0_145
	s_barrier

; #define PG8_STAGE(bufoff, gbase, voff) do { _Pragma("unroll") for (int _i = 0; _i < 2; ++_i) \
;         __builtin_amdgcn_global_load_lds((const unsigned*)((const char*)(gbase) + (voff)[_i]), (LAS unsigned*)(lds + (bufoff) + ldsw + _i * 8192), 16, 0, 0); } while (0)
; #define PG8_LDA(dst, b, h) do { _Pragma("unroll") for (int m = 0; m < 4; ++m) _Pragma("unroll") for (int k = 0; k < 2; ++k) dst[m][k] = *(const LAS bf16x8*)(lds + PG8_SA(b, h) + aoff + m * 2048 + k * 1024); } while (0)
; #define PG8_LDB(dst, b, h) do { _Pragma("unroll") for (int n = 0; n < 2; ++n) _Pragma("unroll") for (int k = 0; k < 2; ++k) dst[n][k] = *(const LAS bf16x8*)(lds + PG8_SB(b, h) + boff + n * 2048 + k * 1024); } while (0)
; #define PG8_MMA(ai, bj, At, Bt) do { __builtin_amdgcn_s_setprio(1); _Pragma("unroll") for (int m = 0; m < 4; ++m) _Pragma("unroll") for (int n = 0; n < 2; ++n) _Pragma("unroll") for (int k = 0; k < 2; ++k) \
;         acc[ai][bj][m][n] = __builtin_amdgcn_mfma_f32_16x16x32_bf16(Bt[n][k], At[m][k], acc[ai][bj][m][n], 0, 0, 0); __builtin_amdgcn_s_setprio(0); } while (0)
; #define PG8_WAIT_L(n) asm volatile("s_waitcnt lgkmcnt(" #n ")" ::: "memory")
; #define PG8_BAR __builtin_amdgcn_s_barrier()
; #define PG8_SCHED __builtin_amdgcn_sched_barrier(0)
; template <class Epi>
; __device__ __forceinline__ void gemm_phase(LAS unsigned char* lds, const Gemm g, const StaticOrder& S, const Epi& E) {
;     ...
;             const bool last = (t == nt - 2);
;             const char* a1 = cA + (size_t)(t + 1) * kstep;
;             const char* a2 = last ? nA : cA + (size_t)(t + 2) * kstep; const char* b2 = last ? nB : cB + (size_t)(t + 2) * kstep;
;             const char* a3 = a2 + kstep; const char* b3 = b2 + kstep;
;             PG8_LDB(B0, 0, 0); PG8_SCHED; PG8_LDA(At, 0, 0); PG8_STAGE(PG8_SA(1, 1), a1 + hstepA, voffA);
;             PG8_WAIT_L(8); PG8_BAR; PG8_WAIT_L(0); PG8_MMA(0, 0, At, B0); PG8_BAR; PG8_SCHED;
;             PG8_LDB(B1, 0, 1); PG8_STAGE(PG8_SB(0, 0), b2, voffB);
;             PG8_BAR; PG8_WAIT_L(0); PG8_MMA(0, 1, At, B1); PG8_BAR;
;             PG8_LDA(At, 0, 1); PG8_STAGE(PG8_SA(0, 0), a2, voffA);
;             PG8_BAR; PG8_WAIT_L(0); PG8_MMA(1, 0, At, B0); PG8_BAR; PG8_SCHED;
.LBB0_187:
	s_mov_b32 s55, 0x10000
	v_add_u32_e32 v140, s55, v207
	ds_read_b128 v[128:131], v140
	ds_read_b128 v[132:135], v140 offset:1024
	ds_read_b128 v[136:139], v140 offset:2048
	ds_read_b128 v[140:143], v140 offset:3072
	ds_read_b128 v[144:147], v209
	ds_read_b128 v[148:151], v209 offset:1024
	ds_read_b128 v[162:165], v209 offset:2048
	ds_read_b128 v[166:169], v209 offset:3072
	ds_read_b128 v[170:173], v209 offset:4096
	ds_read_b128 v[174:177], v209 offset:5120
	ds_read_b128 v[178:181], v209 offset:6144
	ds_read_b128 v[182:185], v209 offset:7168
	s_add_i32 s54, s22, 2
	s_add_u32 s23, s4, 0x4000
	s_addc_u32 s24, s5, 0
	s_cmp_eq_u32 s40, s22
	s_cselect_b32 s26, s6, s23
	s_cselect_b32 s27, s7, s24
	s_cselect_b32 s24, s20, s50
	s_cselect_b32 s25, s21, s51
	s_add_u32 s22, s26, 0x4000
	s_addc_u32 s23, s27, 0
	s_add_i32 m0, s33, 0xc000
	v_lshl_add_u64 v[186:187], s[4:5], 0, v[158:159]
	global_load_lds_dwordx4 v[186:187], off
	s_add_i32 m0, s33, 0xe000
	v_lshl_add_u64 v[186:187], s[4:5], 0, v[160:161]
	global_load_lds_dwordx4 v[186:187], off
	s_waitcnt lgkmcnt(8)
	s_barrier
	s_waitcnt lgkmcnt(0)
	v_mfma_f32_16x16x32_bf16 v[124:127], v[128:131], v[144:147], v[124:127]
	s_setprio 1
	v_mfma_f32_16x16x32_bf16 v[120:123], v[136:139], v[144:147], v[120:123]
	v_mfma_f32_16x16x32_bf16 v[116:119], v[128:131], v[162:165], v[116:119]
	v_mfma_f32_16x16x32_bf16 v[112:115], v[136:139], v[162:165], v[112:115]
	v_mfma_f32_16x16x32_bf16 v[108:111], v[128:131], v[170:173], v[108:111]
	v_mfma_f32_16x16x32_bf16 v[104:107], v[136:139], v[170:173], v[104:107]
	v_mfma_f32_16x16x32_bf16 v[100:103], v[128:131], v[178:181], v[100:103]
	v_mfma_f32_16x16x32_bf16 v[96:99], v[136:139], v[178:181], v[96:99]
	v_mfma_f32_16x16x32_bf16 v[124:127], v[132:135], v[148:151], v[124:127]
	v_mfma_f32_16x16x32_bf16 v[120:123], v[140:143], v[148:151], v[120:123]
	v_mfma_f32_16x16x32_bf16 v[116:119], v[132:135], v[166:169], v[116:119]
	v_mfma_f32_16x16x32_bf16 v[112:115], v[140:143], v[166:169], v[112:115]
	v_mfma_f32_16x16x32_bf16 v[108:111], v[132:135], v[174:177], v[108:111]
	v_mfma_f32_16x16x32_bf16 v[104:107], v[140:143], v[174:177], v[104:107]
	v_mfma_f32_16x16x32_bf16 v[100:103], v[132:135], v[182:185], v[100:103]
	s_setprio 0
	v_mfma_f32_16x16x32_bf16 v[96:99], v[140:143], v[182:185], v[96:99]
	s_barrier
	s_mov_b32 s58, 0x14000
	v_add_u32_e32 v198, s58, v207
	ds_read_b128 v[186:189], v198
	ds_read_b128 v[190:193], v198 offset:1024
	ds_read_b128 v[194:197], v198 offset:2048
	ds_read_b128 v[198:201], v198 offset:3072
	s_add_i32 s55, s55, s31
	s_mov_b32 m0, s55
	v_lshl_add_u64 v[202:203], s[24:25], 0, v[152:153]
	global_load_lds_dwordx4 v[202:203], off
	s_add_i32 m0, s55, 0x2000
	v_lshl_add_u64 v[202:203], s[24:25], 0, v[156:157]
	global_load_lds_dwordx4 v[202:203], off
	s_barrier
	s_waitcnt lgkmcnt(0)
	v_mfma_f32_16x16x32_bf16 v[92:95], v[186:189], v[144:147], v[92:95]
	s_setprio 1
	v_mfma_f32_16x16x32_bf16 v[88:91], v[194:197], v[144:147], v[88:91]
	s_mov_b32 m0, s33
	v_lshl_add_u64 v[202:203], s[26:27], 0, v[152:153]
	v_mfma_f32_16x16x32_bf16 v[84:87], v[186:189], v[162:165], v[84:87]
	v_mfma_f32_16x16x32_bf16 v[80:83], v[194:197], v[162:165], v[80:83]
	v_mfma_f32_16x16x32_bf16 v[76:79], v[186:189], v[170:173], v[76:79]
	v_mfma_f32_16x16x32_bf16 v[72:75], v[194:197], v[170:173], v[72:75]
	v_mfma_f32_16x16x32_bf16 v[68:71], v[186:189], v[178:181], v[68:71]
	v_mfma_f32_16x16x32_bf16 v[64:67], v[194:197], v[178:181], v[64:67]
	v_mfma_f32_16x16x32_bf16 v[92:95], v[190:193], v[148:151], v[92:95]
	v_mfma_f32_16x16x32_bf16 v[88:91], v[198:201], v[148:151], v[88:91]
	v_mfma_f32_16x16x32_bf16 v[84:87], v[190:193], v[166:169], v[84:87]
	v_mfma_f32_16x16x32_bf16 v[80:83], v[198:201], v[166:169], v[80:83]
	v_mfma_f32_16x16x32_bf16 v[76:79], v[190:193], v[174:177], v[76:79]
	v_mfma_f32_16x16x32_bf16 v[72:75], v[198:201], v[174:177], v[72:75]
	v_mfma_f32_16x16x32_bf16 v[68:71], v[190:193], v[182:185], v[68:71]
	s_setprio 0
	v_mfma_f32_16x16x32_bf16 v[64:67], v[198:201], v[182:185], v[64:67]
	s_barrier
	ds_read_b128 v[144:147], v209 offset:16384
	ds_read_b128 v[148:151], v209 offset:17408
	ds_read_b128 v[162:165], v209 offset:18432
	ds_read_b128 v[166:169], v209 offset:19456
	ds_read_b128 v[170:173], v209 offset:20480
	ds_read_b128 v[174:177], v209 offset:21504
	ds_read_b128 v[178:181], v209 offset:22528
	ds_read_b128 v[182:185], v209 offset:23552
	global_load_lds_dwordx4 v[202:203], off
	s_mov_b32 m0, s34
	v_lshl_add_u64 v[202:203], s[26:27], 0, v[156:157]
	global_load_lds_dwordx4 v[202:203], off
	s_barrier
	s_waitcnt lgkmcnt(0)
	v_mfma_f32_16x16x32_bf16 v[60:63], v[128:131], v[144:147], v[60:63]
	s_setprio 1
	v_mfma_f32_16x16x32_bf16 v[56:59], v[136:139], v[144:147], v[56:59]
	v_mfma_f32_16x16x32_bf16 v[52:55], v[128:131], v[162:165], v[52:55]
	v_mfma_f32_16x16x32_bf16 v[48:51], v[136:139], v[162:165], v[48:51]
	v_mfma_f32_16x16x32_bf16 v[44:47], v[128:131], v[170:173], v[44:47]
	v_mfma_f32_16x16x32_bf16 v[40:43], v[136:139], v[170:173], v[40:43]
	v_mfma_f32_16x16x32_bf16 v[36:39], v[128:131], v[178:181], v[36:39]
	v_mfma_f32_16x16x32_bf16 v[32:35], v[136:139], v[178:181], v[32:35]
	v_mfma_f32_16x16x32_bf16 v[60:63], v[132:135], v[148:151], v[60:63]
	v_mfma_f32_16x16x32_bf16 v[56:59], v[140:143], v[148:151], v[56:59]
	v_mfma_f32_16x16x32_bf16 v[52:55], v[132:135], v[166:169], v[52:55]
	v_mfma_f32_16x16x32_bf16 v[48:51], v[140:143], v[166:169], v[48:51]
	v_mfma_f32_16x16x32_bf16 v[44:47], v[132:135], v[174:177], v[44:47]
	v_mfma_f32_16x16x32_bf16 v[40:43], v[140:143], v[174:177], v[40:43]
	v_mfma_f32_16x16x32_bf16 v[36:39], v[132:135], v[182:185], v[36:39]
	s_setprio 0
	v_mfma_f32_16x16x32_bf16 v[32:35], v[140:143], v[182:185], v[32:35]
	s_barrier
; #define PG8_STAGE(bufoff, gbase, voff) do { _Pragma("unroll") for (int _i = 0; _i < 2; ++_i) \
;         __builtin_amdgcn_global_load_lds((const unsigned*)((const char*)(gbase) + (voff)[_i]), (LAS unsigned*)(lds + (bufoff) + ldsw + _i * 8192), 16, 0, 0); } while (0)
; #define PG8_LDA(dst, b, h) do { _Pragma("unroll") for (int m = 0; m < 4; ++m) _Pragma("unroll") for (int k = 0; k < 2; ++k) dst[m][k] = *(const LAS bf16x8*)(lds + PG8_SA(b, h) + aoff + m * 2048 + k * 1024); } while (0)
; #define PG8_LDB(dst, b, h) do { _Pragma("unroll") for (int n = 0; n < 2; ++n) _Pragma("unroll") for (int k = 0; k < 2; ++k) dst[n][k] = *(const LAS bf16x8*)(lds + PG8_SB(b, h) + boff + n * 2048 + k * 1024); } while (0)
; #define PG8_MMA(ai, bj, At, Bt) do { __builtin_amdgcn_s_setprio(1); _Pragma("unroll") for (int m = 0; m < 4; ++m) _Pragma("unroll") for (int n = 0; n < 2; ++n) _Pragma("unroll") for (int k = 0; k < 2; ++k) \
;         acc[ai][bj][m][n] = __builtin_amdgcn_mfma_f32_16x16x32_bf16(Bt[n][k], At[m][k], acc[ai][bj][m][n], 0, 0, 0); __builtin_amdgcn_s_setprio(0); } while (0)
; #define PG8_WAIT_V(n) asm volatile("s_waitcnt vmcnt(" #n ")" ::: "memory")
; #define PG8_WAIT_L(n) asm volatile("s_waitcnt lgkmcnt(" #n ")" ::: "memory")
; #define PG8_BAR __builtin_amdgcn_s_barrier()
; #define PG8_SCHED __builtin_amdgcn_sched_barrier(0)
; template <class Epi>
; __device__ __forceinline__ void gemm_phase(LAS unsigned char* lds, const Gemm g, const StaticOrder& S, const Epi& E) {
;     ...
;             PG8_STAGE(PG8_SB(0, 1), b2 + hstepB, voffB);
;             PG8_WAIT_V(6); PG8_BAR; PG8_MMA(1, 1, At, B1); PG8_BAR;
;             PG8_LDB(B0, 1, 0); PG8_SCHED; PG8_LDA(At, 1, 0); PG8_STAGE(PG8_SA(0, 1), a2 + hstepA, voffA);
;             PG8_WAIT_L(8); PG8_BAR; PG8_WAIT_L(0); PG8_MMA(0, 0, At, B0); PG8_BAR; PG8_SCHED;
;             PG8_LDB(B1, 1, 1); PG8_STAGE(PG8_SB(1, 0), b3, voffB);
;             PG8_BAR; PG8_WAIT_L(0); PG8_MMA(0, 1, At, B1); PG8_BAR;
;             PG8_LDA(At, 1, 1); PG8_STAGE(PG8_SA(1, 0), a3, voffA);
	s_add_u32 s56, s24, s52
	s_addc_u32 s57, s25, 0
	s_add_i32 s55, s58, s31
	s_mov_b32 m0, s55
	v_lshl_add_u64 v[128:129], s[56:57], 0, v[152:153]
	global_load_lds_dwordx4 v[128:129], off
	s_add_i32 m0, s55, 0x2000
	v_lshl_add_u64 v[128:129], s[56:57], 0, v[156:157]
	global_load_lds_dwordx4 v[128:129], off
	s_waitcnt vmcnt(6)
	s_barrier
	v_mfma_f32_16x16x32_bf16 v[28:31], v[186:189], v[144:147], v[28:31]
	s_setprio 1
	v_mfma_f32_16x16x32_bf16 v[24:27], v[194:197], v[144:147], v[24:27]
	s_add_i32 s55, 0, 0x18000
	v_add_u32_e32 v140, s55, v207
	v_mfma_f32_16x16x32_bf16 v[20:23], v[186:189], v[162:165], v[20:23]
	v_mfma_f32_16x16x32_bf16 v[16:19], v[194:197], v[162:165], v[16:19]
	v_mfma_f32_16x16x32_bf16 v[12:15], v[186:189], v[170:173], v[12:15]
	v_mfma_f32_16x16x32_bf16 v[8:11], v[194:197], v[170:173], v[8:11]
	v_mfma_f32_16x16x32_bf16 v[4:7], v[186:189], v[178:181], v[4:7]
	v_mfma_f32_16x16x32_bf16 v[0:3], v[194:197], v[178:181], v[0:3]
	v_mfma_f32_16x16x32_bf16 v[28:31], v[190:193], v[148:151], v[28:31]
	v_mfma_f32_16x16x32_bf16 v[24:27], v[198:201], v[148:151], v[24:27]
	v_mfma_f32_16x16x32_bf16 v[20:23], v[190:193], v[166:169], v[20:23]
	v_mfma_f32_16x16x32_bf16 v[16:19], v[198:201], v[166:169], v[16:19]
	v_mfma_f32_16x16x32_bf16 v[12:15], v[190:193], v[174:177], v[12:15]
	v_mfma_f32_16x16x32_bf16 v[8:11], v[198:201], v[174:177], v[8:11]
	v_mfma_f32_16x16x32_bf16 v[4:7], v[190:193], v[182:185], v[4:7]
	s_setprio 0
	v_mfma_f32_16x16x32_bf16 v[0:3], v[198:201], v[182:185], v[0:3]
	s_barrier
	ds_read_b128 v[128:131], v140
	ds_read_b128 v[132:135], v140 offset:1024
	ds_read_b128 v[136:139], v140 offset:2048
	ds_read_b128 v[140:143], v140 offset:3072
	ds_read_b128 v[144:147], v209 offset:32768
	ds_read_b128 v[148:151], v209 offset:33792
	ds_read_b128 v[162:165], v209 offset:34816
	ds_read_b128 v[166:169], v209 offset:35840
	ds_read_b128 v[170:173], v209 offset:36864
	ds_read_b128 v[174:177], v209 offset:37888
	ds_read_b128 v[178:181], v209 offset:38912
	ds_read_b128 v[182:185], v209 offset:39936
	s_add_u32 s26, s26, s52
	s_addc_u32 s27, s27, 0
	s_mov_b32 m0, s35
	v_lshl_add_u64 v[186:187], s[26:27], 0, v[152:153]
	global_load_lds_dwordx4 v[186:187], off
	s_mov_b32 m0, s36
	v_lshl_add_u64 v[186:187], s[26:27], 0, v[156:157]
	global_load_lds_dwordx4 v[186:187], off
	s_waitcnt lgkmcnt(8)
	s_barrier
	s_waitcnt lgkmcnt(0)
	v_mfma_f32_16x16x32_bf16 v[124:127], v[128:131], v[144:147], v[124:127]
	s_setprio 1
	v_mfma_f32_16x16x32_bf16 v[120:123], v[136:139], v[144:147], v[120:123]
	v_mfma_f32_16x16x32_bf16 v[116:119], v[128:131], v[162:165], v[116:119]
	v_mfma_f32_16x16x32_bf16 v[112:115], v[136:139], v[162:165], v[112:115]
	v_mfma_f32_16x16x32_bf16 v[108:111], v[128:131], v[170:173], v[108:111]
	v_mfma_f32_16x16x32_bf16 v[104:107], v[136:139], v[170:173], v[104:107]
	v_mfma_f32_16x16x32_bf16 v[100:103], v[128:131], v[178:181], v[100:103]
	v_mfma_f32_16x16x32_bf16 v[96:99], v[136:139], v[178:181], v[96:99]
	v_mfma_f32_16x16x32_bf16 v[124:127], v[132:135], v[148:151], v[124:127]
	v_mfma_f32_16x16x32_bf16 v[120:123], v[140:143], v[148:151], v[120:123]
	v_mfma_f32_16x16x32_bf16 v[116:119], v[132:135], v[166:169], v[116:119]
	v_mfma_f32_16x16x32_bf16 v[112:115], v[140:143], v[166:169], v[112:115]
	v_mfma_f32_16x16x32_bf16 v[108:111], v[132:135], v[174:177], v[108:111]
	v_mfma_f32_16x16x32_bf16 v[104:107], v[140:143], v[174:177], v[104:107]
	v_mfma_f32_16x16x32_bf16 v[100:103], v[132:135], v[182:185], v[100:103]
	s_setprio 0
	v_mfma_f32_16x16x32_bf16 v[96:99], v[140:143], v[182:185], v[96:99]
	s_barrier
	s_mov_b32 s26, 0x1c000
	v_add_u32_e32 v198, s26, v207
	ds_read_b128 v[186:189], v198
	ds_read_b128 v[190:193], v198 offset:1024
	ds_read_b128 v[194:197], v198 offset:2048
	ds_read_b128 v[198:201], v198 offset:3072
	s_add_u32 s24, s24, 0x4000
	s_addc_u32 s25, s25, 0
	s_add_i32 s27, s55, s31
	s_mov_b32 m0, s27
	v_lshl_add_u64 v[202:203], s[24:25], 0, v[152:153]
	global_load_lds_dwordx4 v[202:203], off
	s_add_i32 m0, s27, 0x2000
	v_lshl_add_u64 v[202:203], s[24:25], 0, v[156:157]
	global_load_lds_dwordx4 v[202:203], off
	s_barrier
; #define PG8_STAGE(bufoff, gbase, voff) do { _Pragma("unroll") for (int _i = 0; _i < 2; ++_i) \
;         __builtin_amdgcn_global_load_lds((const unsigned*)((const char*)(gbase) + (voff)[_i]), (LAS unsigned*)(lds + (bufoff) + ldsw + _i * 8192), 16, 0, 0); } while (0)
; #define PG8_MMA(ai, bj, At, Bt) do { __builtin_amdgcn_s_setprio(1); _Pragma("unroll") for (int m = 0; m < 4; ++m) _Pragma("unroll") for (int n = 0; n < 2; ++n) _Pragma("unroll") for (int k = 0; k < 2; ++k) \
;         acc[ai][bj][m][n] = __builtin_amdgcn_mfma_f32_16x16x32_bf16(Bt[n][k], At[m][k], acc[ai][bj][m][n], 0, 0, 0); __builtin_amdgcn_s_setprio(0); } while (0)
; #define PG8_WAIT_V(n) asm volatile("s_waitcnt vmcnt(" #n ")" ::: "memory")
; #define PG8_WAIT_L(n) asm volatile("s_waitcnt lgkmcnt(" #n ")" ::: "memory")
; #define PG8_BAR __builtin_amdgcn_s_barrier()
; #define PG8_SCHED __builtin_amdgcn_sched_barrier(0)
; template <class Epi>
; __device__ __forceinline__ void gemm_phase(LAS unsigned char* lds, const Gemm g, const StaticOrder& S, const Epi& E) {
;     ...
;             PG8_BAR; PG8_WAIT_L(0); PG8_MMA(1, 0, At, B0); PG8_BAR; PG8_SCHED;
;             PG8_STAGE(PG8_SB(1, 1), b3 + hstepB, voffB);
;             PG8_WAIT_V(6); PG8_BAR; PG8_MMA(1, 1, At, B1); PG8_BAR;
;     __device__ __forceinline__ void operator()(const f32x4 (&acc)[2][2][4][2], const Unit& u, int wr, int wc, int fr, int fq) const {
;         const int row0 = u.pm * BM + wr * 64 + fr, col0 = u.pn * BM + wc * 32 + 8 * fq;
;         const float* gb = gate + (size_t)(row0 >> 12) * (6 * DM);
;         const bool ln = stats != nullptr;
;         constexpr int GB[4] = {0, 4, 8, 16};
;         f32x2 st[4];
; #pragma unroll
;         for (int grp = 0; grp < 3; ++grp) {
;             u32x4 xv[8]; f32x4 cg[2][2], cl[2][2], cb[2][2];
;             if (grp == 0 || grp == 2) {
; #pragma unroll
;                 for (int m = 0; m < 4; ++m) st[m] = ln ? *(const f32x2*)(stats + 2 * (row0 + (grp ? HALF : 0) + m * 16)) : (f32x2){0.f, 1.f};
	s_waitcnt lgkmcnt(0)
	v_mfma_f32_16x16x32_bf16 v[92:95], v[186:189], v[144:147], v[92:95]
	s_setprio 1
	v_mfma_f32_16x16x32_bf16 v[88:91], v[194:197], v[144:147], v[88:91]
	s_mov_b32 m0, s38
	v_lshl_add_u64 v[202:203], s[22:23], 0, v[152:153]
	v_mfma_f32_16x16x32_bf16 v[84:87], v[186:189], v[162:165], v[84:87]
	v_mfma_f32_16x16x32_bf16 v[80:83], v[194:197], v[162:165], v[80:83]
	v_mfma_f32_16x16x32_bf16 v[76:79], v[186:189], v[170:173], v[76:79]
	v_mfma_f32_16x16x32_bf16 v[72:75], v[194:197], v[170:173], v[72:75]
	v_mfma_f32_16x16x32_bf16 v[68:71], v[186:189], v[178:181], v[68:71]
	v_mfma_f32_16x16x32_bf16 v[64:67], v[194:197], v[178:181], v[64:67]
	v_mfma_f32_16x16x32_bf16 v[92:95], v[190:193], v[148:151], v[92:95]
	v_mfma_f32_16x16x32_bf16 v[88:91], v[198:201], v[148:151], v[88:91]
	v_mfma_f32_16x16x32_bf16 v[84:87], v[190:193], v[166:169], v[84:87]
	v_mfma_f32_16x16x32_bf16 v[80:83], v[198:201], v[166:169], v[80:83]
	v_mfma_f32_16x16x32_bf16 v[76:79], v[190:193], v[174:177], v[76:79]
	v_mfma_f32_16x16x32_bf16 v[72:75], v[198:201], v[174:177], v[72:75]
	v_mfma_f32_16x16x32_bf16 v[68:71], v[190:193], v[182:185], v[68:71]
	s_setprio 0
	v_mfma_f32_16x16x32_bf16 v[64:67], v[198:201], v[182:185], v[64:67]
	s_barrier
	ds_read_b128 v[144:147], v209 offset:49152
	ds_read_b128 v[148:151], v209 offset:50176
	ds_read_b128 v[162:165], v209 offset:51200
	ds_read_b128 v[166:169], v209 offset:52224
	ds_read_b128 v[170:173], v209 offset:53248
	ds_read_b128 v[174:177], v209 offset:54272
	ds_read_b128 v[178:181], v209 offset:55296
	ds_read_b128 v[182:185], v209 offset:56320
	global_load_lds_dwordx4 v[202:203], off
	s_mov_b32 m0, s39
	v_lshl_add_u64 v[202:203], s[22:23], 0, v[156:157]
	global_load_lds_dwordx4 v[202:203], off
	s_barrier
	s_waitcnt lgkmcnt(0)
	v_mfma_f32_16x16x32_bf16 v[60:63], v[128:131], v[144:147], v[60:63]
	s_setprio 1
	v_mfma_f32_16x16x32_bf16 v[56:59], v[136:139], v[144:147], v[56:59]
	v_mfma_f32_16x16x32_bf16 v[52:55], v[128:131], v[162:165], v[52:55]
	v_mfma_f32_16x16x32_bf16 v[48:51], v[136:139], v[162:165], v[48:51]
	v_mfma_f32_16x16x32_bf16 v[44:47], v[128:131], v[170:173], v[44:47]
	v_mfma_f32_16x16x32_bf16 v[40:43], v[136:139], v[170:173], v[40:43]
	v_mfma_f32_16x16x32_bf16 v[36:39], v[128:131], v[178:181], v[36:39]
	v_mfma_f32_16x16x32_bf16 v[32:35], v[136:139], v[178:181], v[32:35]
	v_mfma_f32_16x16x32_bf16 v[60:63], v[132:135], v[148:151], v[60:63]
	v_mfma_f32_16x16x32_bf16 v[56:59], v[140:143], v[148:151], v[56:59]
	v_mfma_f32_16x16x32_bf16 v[52:55], v[132:135], v[166:169], v[52:55]
	v_mfma_f32_16x16x32_bf16 v[48:51], v[140:143], v[166:169], v[48:51]
	v_mfma_f32_16x16x32_bf16 v[44:47], v[132:135], v[174:177], v[44:47]
	v_mfma_f32_16x16x32_bf16 v[40:43], v[140:143], v[174:177], v[40:43]
	v_mfma_f32_16x16x32_bf16 v[36:39], v[132:135], v[182:185], v[36:39]
	s_setprio 0
	v_mfma_f32_16x16x32_bf16 v[32:35], v[140:143], v[182:185], v[32:35]
	s_barrier
	s_add_u32 s22, s24, s52
	s_addc_u32 s23, s25, 0
	s_add_i32 s24, s26, s31
	s_mov_b32 m0, s24
	v_lshl_add_u64 v[128:129], s[22:23], 0, v[152:153]
	global_load_lds_dwordx4 v[128:129], off
	s_add_i32 m0, s24, 0x2000
	v_lshl_add_u64 v[128:129], s[22:23], 0, v[156:157]
	global_load_lds_dwordx4 v[128:129], off
	s_waitcnt vmcnt(6)
	s_barrier
	v_mfma_f32_16x16x32_bf16 v[28:31], v[186:189], v[144:147], v[28:31]
	s_setprio 1
	v_mfma_f32_16x16x32_bf16 v[24:27], v[194:197], v[144:147], v[24:27]
	s_add_u32 s4, s4, 0x8000
	s_addc_u32 s5, s5, 0
	s_add_u32 s50, s50, 0x8000
	s_addc_u32 s51, s51, 0
	v_mfma_f32_16x16x32_bf16 v[20:23], v[186:189], v[162:165], v[20:23]
	v_mfma_f32_16x16x32_bf16 v[16:19], v[194:197], v[162:165], v[16:19]
	v_mfma_f32_16x16x32_bf16 v[12:15], v[186:189], v[170:173], v[12:15]
	v_mfma_f32_16x16x32_bf16 v[8:11], v[194:197], v[170:173], v[8:11]
	v_mfma_f32_16x16x32_bf16 v[4:7], v[186:189], v[178:181], v[4:7]
	v_mfma_f32_16x16x32_bf16 v[0:3], v[194:197], v[178:181], v[0:3]
	v_mfma_f32_16x16x32_bf16 v[28:31], v[190:193], v[148:151], v[28:31]
	v_mfma_f32_16x16x32_bf16 v[24:27], v[198:201], v[148:151], v[24:27]
	v_mfma_f32_16x16x32_bf16 v[20:23], v[190:193], v[166:169], v[20:23]
	v_mfma_f32_16x16x32_bf16 v[16:19], v[198:201], v[166:169], v[16:19]
	v_mfma_f32_16x16x32_bf16 v[12:15], v[190:193], v[174:177], v[12:15]
	v_mfma_f32_16x16x32_bf16 v[8:11], v[198:201], v[174:177], v[8:11]
	v_mfma_f32_16x16x32_bf16 v[4:7], v[190:193], v[182:185], v[4:7]
	s_cmp_ge_u32 s54, s28
	s_mov_b32 s22, s54
	s_setprio 0
	v_mfma_f32_16x16x32_bf16 v[0:3], v[198:201], v[182:185], v[0:3]
	s_barrier
	s_cbranch_scc0 .LBB0_187
	s_lshl_b32 s22, s49, 8
	s_add_i32 s22, s22, s37
	v_or_b32_e32 v162, s22, v206
	v_lshlrev_b32_e32 v170, 1, v162
	v_cndmask_b32_e64 v128, 0, 1, s[12:13]
	v_mov_b32_e32 v182, 1.0
	v_mov_b32_e32 v184, 0
	v_cmp_ne_u32_e64 s[4:5], 1, v128
	s_andn2_b64 vcc, exec, s[12:13]
	v_ashrrev_i32_e32 v171, 31, v170
	v_mov_b32_e32 v192, 0
	v_mov_b32_e32 v194, 1.0
	s_cbranch_vccnz .LBB0_190
	v_lshl_add_u64 v[128:129], v[170:171], 2, s[14:15]
	global_load_dwordx2 v[192:193], v[128:129], off
	s_waitcnt vmcnt(0)
	v_mov_b32_e32 v194, v193

; #define PG8_STAGE(bufoff, gbase, voff) do { _Pragma("unroll") for (int _i = 0; _i < 2; ++_i) \
;         __builtin_amdgcn_global_load_lds((const unsigned*)((const char*)(gbase) + (voff)[_i]), (LAS unsigned*)(lds + (bufoff) + ldsw + _i * 8192), 16, 0, 0); } while (0)
; #define PG8_LDA(dst, b, h) do { _Pragma("unroll") for (int m = 0; m < 4; ++m) _Pragma("unroll") for (int k = 0; k < 2; ++k) dst[m][k] = *(const LAS bf16x8*)(lds + PG8_SA(b, h) + aoff + m * 2048 + k * 1024); } while (0)
; #define PG8_LDB(dst, b, h) do { _Pragma("unroll") for (int n = 0; n < 2; ++n) _Pragma("unroll") for (int k = 0; k < 2; ++k) dst[n][k] = *(const LAS bf16x8*)(lds + PG8_SB(b, h) + boff + n * 2048 + k * 1024); } while (0)
; #define PG8_MMA(ai, bj, At, Bt) do { __builtin_amdgcn_s_setprio(1); _Pragma("unroll") for (int m = 0; m < 4; ++m) _Pragma("unroll") for (int n = 0; n < 2; ++n) _Pragma("unroll") for (int k = 0; k < 2; ++k) \
;         acc[ai][bj][m][n] = __builtin_amdgcn_mfma_f32_16x16x32_bf16(Bt[n][k], At[m][k], acc[ai][bj][m][n], 0, 0, 0); __builtin_amdgcn_s_setprio(0); } while (0)
; #define PG8_WAIT_L(n) asm volatile("s_waitcnt lgkmcnt(" #n ")" ::: "memory")
; #define PG8_BAR __builtin_amdgcn_s_barrier()
; #define PG8_SCHED __builtin_amdgcn_sched_barrier(0)
; template <class Epi>
; __device__ __forceinline__ void gemm_phase(LAS unsigned char* lds, const Gemm g, const StaticOrder& S, const Epi& E) {
;     ...
;             const bool last = (t == nt - 2);
;             const char* a1 = cA + (size_t)(t + 1) * kstep;
;             const char* a2 = last ? nA : cA + (size_t)(t + 2) * kstep; const char* b2 = last ? nB : cB + (size_t)(t + 2) * kstep;
;             const char* a3 = a2 + kstep; const char* b3 = b2 + kstep;
;             PG8_LDB(B0, 0, 0); PG8_SCHED; PG8_LDA(At, 0, 0); PG8_STAGE(PG8_SA(1, 1), a1 + hstepA, voffA);
;             PG8_WAIT_L(8); PG8_BAR; PG8_WAIT_L(0); PG8_MMA(0, 0, At, B0); PG8_BAR; PG8_SCHED;
;             PG8_LDB(B1, 0, 1); PG8_STAGE(PG8_SB(0, 0), b2, voffB);
;             PG8_BAR; PG8_WAIT_L(0); PG8_MMA(0, 1, At, B1); PG8_BAR;
;             PG8_LDA(At, 0, 1); PG8_STAGE(PG8_SA(0, 0), a2, voffA);
;             PG8_BAR; PG8_WAIT_L(0); PG8_MMA(1, 0, At, B0); PG8_BAR; PG8_SCHED;
.LBB0_247:
	s_mov_b32 s39, 0x10000
	v_add_u32_e32 v140, s39, v170
	ds_read_b128 v[128:131], v140
	ds_read_b128 v[132:135], v140 offset:1024
	ds_read_b128 v[136:139], v140 offset:2048
	ds_read_b128 v[140:143], v140 offset:3072
	ds_read_b128 v[144:147], v172
	ds_read_b128 v[148:151], v172 offset:1024
	ds_read_b128 v[166:169], v172 offset:2048
	ds_read_b128 v[174:177], v172 offset:3072
	ds_read_b128 v[178:181], v172 offset:4096
	ds_read_b128 v[182:185], v172 offset:5120
	ds_read_b128 v[186:189], v172 offset:6144
	ds_read_b128 v[190:193], v172 offset:7168
	s_add_u32 s14, s12, 0xfff84000
	s_addc_u32 s15, s13, -1
	s_cmp_eq_u32 s38, 28
	s_cselect_b32 s18, s11, s14
	s_cselect_b32 s19, s5, s15
	s_cselect_b32 s14, s35, s36
	s_cselect_b32 s15, s3, s37
	s_add_u32 s16, s18, 0x4000
	s_addc_u32 s17, s19, 0
	s_add_i32 m0, s25, 0xc000
	v_lshl_add_u64 v[194:195], s[12:13], 0, v[156:157]
	global_load_lds_dwordx4 v[194:195], off
	s_add_i32 m0, s25, 0xe000
	v_lshl_add_u64 v[194:195], s[12:13], 0, v[158:159]
	global_load_lds_dwordx4 v[194:195], off
	s_waitcnt lgkmcnt(8)
	s_barrier
	s_waitcnt lgkmcnt(0)
	v_mfma_f32_16x16x32_bf16 v[124:127], v[128:131], v[144:147], v[124:127]
	s_setprio 1
	v_mfma_f32_16x16x32_bf16 v[120:123], v[136:139], v[144:147], v[120:123]
	v_mfma_f32_16x16x32_bf16 v[108:111], v[128:131], v[166:169], v[108:111]
	v_mfma_f32_16x16x32_bf16 v[104:107], v[136:139], v[166:169], v[104:107]
	v_mfma_f32_16x16x32_bf16 v[92:95], v[128:131], v[178:181], v[92:95]
	v_mfma_f32_16x16x32_bf16 v[88:91], v[136:139], v[178:181], v[88:91]
	v_mfma_f32_16x16x32_bf16 v[76:79], v[128:131], v[186:189], v[76:79]
	v_mfma_f32_16x16x32_bf16 v[72:75], v[136:139], v[186:189], v[72:75]
	v_mfma_f32_16x16x32_bf16 v[124:127], v[132:135], v[148:151], v[124:127]
	v_mfma_f32_16x16x32_bf16 v[120:123], v[140:143], v[148:151], v[120:123]
	v_mfma_f32_16x16x32_bf16 v[108:111], v[132:135], v[174:177], v[108:111]
	v_mfma_f32_16x16x32_bf16 v[104:107], v[140:143], v[174:177], v[104:107]
	v_mfma_f32_16x16x32_bf16 v[92:95], v[132:135], v[182:185], v[92:95]
	v_mfma_f32_16x16x32_bf16 v[88:91], v[140:143], v[182:185], v[88:91]
	v_mfma_f32_16x16x32_bf16 v[76:79], v[132:135], v[190:193], v[76:79]
	s_setprio 0
	v_mfma_f32_16x16x32_bf16 v[72:75], v[140:143], v[190:193], v[72:75]
	s_barrier
	s_mov_b32 s42, 0x14000
	v_add_u32_e32 v152, s42, v170
	ds_read_b128 v[194:197], v152
	ds_read_b128 v[198:201], v152 offset:1024
	ds_read_b128 v[202:205], v152 offset:2048
	ds_read_b128 v[206:209], v152 offset:3072
	s_add_i32 s39, s39, s23
	s_mov_b32 m0, s39
	v_lshl_add_u64 v[210:211], s[14:15], 0, v[156:157]
	global_load_lds_dwordx4 v[210:211], off
	s_add_i32 m0, s39, 0x2000
	v_lshl_add_u64 v[210:211], s[14:15], 0, v[158:159]
	global_load_lds_dwordx4 v[210:211], off
	s_barrier
	s_waitcnt lgkmcnt(0)
	v_mfma_f32_16x16x32_bf16 v[116:119], v[194:197], v[144:147], v[116:119]
	s_setprio 1
	v_mfma_f32_16x16x32_bf16 v[112:115], v[202:205], v[144:147], v[112:115]
	s_mov_b32 m0, s25
	v_lshl_add_u64 v[210:211], s[18:19], 0, v[156:157]
	v_mfma_f32_16x16x32_bf16 v[100:103], v[194:197], v[166:169], v[100:103]
	v_mfma_f32_16x16x32_bf16 v[96:99], v[202:205], v[166:169], v[96:99]
	v_mfma_f32_16x16x32_bf16 v[84:87], v[194:197], v[178:181], v[84:87]
	v_mfma_f32_16x16x32_bf16 v[80:83], v[202:205], v[178:181], v[80:83]
	v_mfma_f32_16x16x32_bf16 v[68:71], v[194:197], v[186:189], v[68:71]
	v_mfma_f32_16x16x32_bf16 v[64:67], v[202:205], v[186:189], v[64:67]
	v_mfma_f32_16x16x32_bf16 v[116:119], v[198:201], v[148:151], v[116:119]
	v_mfma_f32_16x16x32_bf16 v[112:115], v[206:209], v[148:151], v[112:115]
	v_mfma_f32_16x16x32_bf16 v[100:103], v[198:201], v[174:177], v[100:103]
	v_mfma_f32_16x16x32_bf16 v[96:99], v[206:209], v[174:177], v[96:99]
	v_mfma_f32_16x16x32_bf16 v[84:87], v[198:201], v[182:185], v[84:87]
	v_mfma_f32_16x16x32_bf16 v[80:83], v[206:209], v[182:185], v[80:83]
	v_mfma_f32_16x16x32_bf16 v[68:71], v[198:201], v[190:193], v[68:71]
	s_setprio 0
	v_mfma_f32_16x16x32_bf16 v[64:67], v[206:209], v[190:193], v[64:67]
	s_barrier
	ds_read_b128 v[144:147], v172 offset:16384
	ds_read_b128 v[148:151], v172 offset:17408
	ds_read_b128 v[166:169], v172 offset:18432
	ds_read_b128 v[174:177], v172 offset:19456
	ds_read_b128 v[178:181], v172 offset:20480
	ds_read_b128 v[182:185], v172 offset:21504
	ds_read_b128 v[186:189], v172 offset:22528
	ds_read_b128 v[190:193], v172 offset:23552
	global_load_lds_dwordx4 v[210:211], off
	s_mov_b32 m0, s26
	v_lshl_add_u64 v[210:211], s[18:19], 0, v[158:159]
	global_load_lds_dwordx4 v[210:211], off
	s_barrier
	s_waitcnt lgkmcnt(0)
	v_mfma_f32_16x16x32_bf16 v[60:63], v[128:131], v[144:147], v[60:63]
	s_setprio 1
	v_mfma_f32_16x16x32_bf16 v[56:59], v[136:139], v[144:147], v[56:59]
	v_mfma_f32_16x16x32_bf16 v[44:47], v[128:131], v[166:169], v[44:47]
	v_mfma_f32_16x16x32_bf16 v[40:43], v[136:139], v[166:169], v[40:43]
	v_mfma_f32_16x16x32_bf16 v[28:31], v[128:131], v[178:181], v[28:31]
	v_mfma_f32_16x16x32_bf16 v[24:27], v[136:139], v[178:181], v[24:27]
	v_mfma_f32_16x16x32_bf16 v[12:15], v[128:131], v[186:189], v[12:15]
	v_mfma_f32_16x16x32_bf16 v[8:11], v[136:139], v[186:189], v[8:11]
	v_mfma_f32_16x16x32_bf16 v[60:63], v[132:135], v[148:151], v[60:63]
	v_mfma_f32_16x16x32_bf16 v[56:59], v[140:143], v[148:151], v[56:59]
	v_mfma_f32_16x16x32_bf16 v[44:47], v[132:135], v[174:177], v[44:47]
	v_mfma_f32_16x16x32_bf16 v[40:43], v[140:143], v[174:177], v[40:43]
	v_mfma_f32_16x16x32_bf16 v[28:31], v[132:135], v[182:185], v[28:31]
	v_mfma_f32_16x16x32_bf16 v[24:27], v[140:143], v[182:185], v[24:27]
	v_mfma_f32_16x16x32_bf16 v[12:15], v[132:135], v[190:193], v[12:15]
	s_setprio 0
	v_mfma_f32_16x16x32_bf16 v[8:11], v[140:143], v[190:193], v[8:11]
	s_barrier
; #define PG8_STAGE(bufoff, gbase, voff) do { _Pragma("unroll") for (int _i = 0; _i < 2; ++_i) \
;         __builtin_amdgcn_global_load_lds((const unsigned*)((const char*)(gbase) + (voff)[_i]), (LAS unsigned*)(lds + (bufoff) + ldsw + _i * 8192), 16, 0, 0); } while (0)
; #define PG8_LDA(dst, b, h) do { _Pragma("unroll") for (int m = 0; m < 4; ++m) _Pragma("unroll") for (int k = 0; k < 2; ++k) dst[m][k] = *(const LAS bf16x8*)(lds + PG8_SA(b, h) + aoff + m * 2048 + k * 1024); } while (0)
; #define PG8_LDB(dst, b, h) do { _Pragma("unroll") for (int n = 0; n < 2; ++n) _Pragma("unroll") for (int k = 0; k < 2; ++k) dst[n][k] = *(const LAS bf16x8*)(lds + PG8_SB(b, h) + boff + n * 2048 + k * 1024); } while (0)
; #define PG8_MMA(ai, bj, At, Bt) do { __builtin_amdgcn_s_setprio(1); _Pragma("unroll") for (int m = 0; m < 4; ++m) _Pragma("unroll") for (int n = 0; n < 2; ++n) _Pragma("unroll") for (int k = 0; k < 2; ++k) \
;         acc[ai][bj][m][n] = __builtin_amdgcn_mfma_f32_16x16x32_bf16(Bt[n][k], At[m][k], acc[ai][bj][m][n], 0, 0, 0); __builtin_amdgcn_s_setprio(0); } while (0)
; #define PG8_WAIT_V(n) asm volatile("s_waitcnt vmcnt(" #n ")" ::: "memory")
; #define PG8_WAIT_L(n) asm volatile("s_waitcnt lgkmcnt(" #n ")" ::: "memory")
; #define PG8_BAR __builtin_amdgcn_s_barrier()
; #define PG8_SCHED __builtin_amdgcn_sched_barrier(0)
; template <class Epi>
; __device__ __forceinline__ void gemm_phase(LAS unsigned char* lds, const Gemm g, const StaticOrder& S, const Epi& E) {
;     ...
;             PG8_STAGE(PG8_SB(0, 1), b2 + hstepB, voffB);
;             PG8_WAIT_V(6); PG8_BAR; PG8_MMA(1, 1, At, B1); PG8_BAR;
;             PG8_LDB(B0, 1, 0); PG8_SCHED; PG8_LDA(At, 1, 0); PG8_STAGE(PG8_SA(0, 1), a2 + hstepA, voffA);
;             PG8_WAIT_L(8); PG8_BAR; PG8_WAIT_L(0); PG8_MMA(0, 0, At, B0); PG8_BAR; PG8_SCHED;
;             PG8_LDB(B1, 1, 1); PG8_STAGE(PG8_SB(1, 0), b3, voffB);
;             PG8_BAR; PG8_WAIT_L(0); PG8_MMA(0, 1, At, B1); PG8_BAR;
;             PG8_LDA(At, 1, 1); PG8_STAGE(PG8_SA(1, 0), a3, voffA);
;             PG8_BAR; PG8_WAIT_L(0); PG8_MMA(1, 0, At, B0); PG8_BAR; PG8_SCHED;
	s_add_u32 s40, s14, 0x80000
	s_addc_u32 s41, s15, 0
	s_add_i32 s39, s42, s23
	s_mov_b32 m0, s39
	v_lshl_add_u64 v[128:129], s[40:41], 0, v[156:157]
	global_load_lds_dwordx4 v[128:129], off
	s_add_i32 m0, s39, 0x2000
	v_lshl_add_u64 v[128:129], s[40:41], 0, v[158:159]
	global_load_lds_dwordx4 v[128:129], off
	s_waitcnt vmcnt(6)
	s_barrier
	v_mfma_f32_16x16x32_bf16 v[52:55], v[194:197], v[144:147], v[52:55]
	s_setprio 1
	v_mfma_f32_16x16x32_bf16 v[48:51], v[202:205], v[144:147], v[48:51]
	s_add_i32 s39, 0, 0x18000
	v_add_u32_e32 v140, s39, v170
	v_mfma_f32_16x16x32_bf16 v[36:39], v[194:197], v[166:169], v[36:39]
	v_mfma_f32_16x16x32_bf16 v[32:35], v[202:205], v[166:169], v[32:35]
	v_mfma_f32_16x16x32_bf16 v[20:23], v[194:197], v[178:181], v[20:23]
	v_mfma_f32_16x16x32_bf16 v[16:19], v[202:205], v[178:181], v[16:19]
	v_mfma_f32_16x16x32_bf16 v[4:7], v[194:197], v[186:189], v[4:7]
	v_mfma_f32_16x16x32_bf16 v[0:3], v[202:205], v[186:189], v[0:3]
	v_mfma_f32_16x16x32_bf16 v[52:55], v[198:201], v[148:151], v[52:55]
	v_mfma_f32_16x16x32_bf16 v[48:51], v[206:209], v[148:151], v[48:51]
	v_mfma_f32_16x16x32_bf16 v[36:39], v[198:201], v[174:177], v[36:39]
	v_mfma_f32_16x16x32_bf16 v[32:35], v[206:209], v[174:177], v[32:35]
	v_mfma_f32_16x16x32_bf16 v[20:23], v[198:201], v[182:185], v[20:23]
	v_mfma_f32_16x16x32_bf16 v[16:19], v[206:209], v[182:185], v[16:19]
	v_mfma_f32_16x16x32_bf16 v[4:7], v[198:201], v[190:193], v[4:7]
	s_setprio 0
	v_mfma_f32_16x16x32_bf16 v[0:3], v[206:209], v[190:193], v[0:3]
	s_barrier
	ds_read_b128 v[128:131], v140
	ds_read_b128 v[132:135], v140 offset:1024
	ds_read_b128 v[136:139], v140 offset:2048
	ds_read_b128 v[140:143], v140 offset:3072
	ds_read_b128 v[144:147], v172 offset:32768
	ds_read_b128 v[148:151], v172 offset:33792
	ds_read_b128 v[166:169], v172 offset:34816
	ds_read_b128 v[174:177], v172 offset:35840
	ds_read_b128 v[178:181], v172 offset:36864
	ds_read_b128 v[182:185], v172 offset:37888
	ds_read_b128 v[186:189], v172 offset:38912
	ds_read_b128 v[190:193], v172 offset:39936
	s_add_u32 s18, s18, 0x80000
	s_addc_u32 s19, s19, 0
	s_mov_b32 m0, s27
	v_lshl_add_u64 v[194:195], s[18:19], 0, v[156:157]
	global_load_lds_dwordx4 v[194:195], off
	s_mov_b32 m0, s28
	v_lshl_add_u64 v[194:195], s[18:19], 0, v[158:159]
	global_load_lds_dwordx4 v[194:195], off
	s_waitcnt lgkmcnt(8)
	s_barrier
	s_waitcnt lgkmcnt(0)
	v_mfma_f32_16x16x32_bf16 v[124:127], v[128:131], v[144:147], v[124:127]
	s_setprio 1
	v_mfma_f32_16x16x32_bf16 v[120:123], v[136:139], v[144:147], v[120:123]
	v_mfma_f32_16x16x32_bf16 v[108:111], v[128:131], v[166:169], v[108:111]
	v_mfma_f32_16x16x32_bf16 v[104:107], v[136:139], v[166:169], v[104:107]
	v_mfma_f32_16x16x32_bf16 v[92:95], v[128:131], v[178:181], v[92:95]
	v_mfma_f32_16x16x32_bf16 v[88:91], v[136:139], v[178:181], v[88:91]
	v_mfma_f32_16x16x32_bf16 v[76:79], v[128:131], v[186:189], v[76:79]
	v_mfma_f32_16x16x32_bf16 v[72:75], v[136:139], v[186:189], v[72:75]
	v_mfma_f32_16x16x32_bf16 v[124:127], v[132:135], v[148:151], v[124:127]
	v_mfma_f32_16x16x32_bf16 v[120:123], v[140:143], v[148:151], v[120:123]
	v_mfma_f32_16x16x32_bf16 v[108:111], v[132:135], v[174:177], v[108:111]
	v_mfma_f32_16x16x32_bf16 v[104:107], v[140:143], v[174:177], v[104:107]
	v_mfma_f32_16x16x32_bf16 v[92:95], v[132:135], v[182:185], v[92:95]
	v_mfma_f32_16x16x32_bf16 v[88:91], v[140:143], v[182:185], v[88:91]
	v_mfma_f32_16x16x32_bf16 v[76:79], v[132:135], v[190:193], v[76:79]
	s_setprio 0
	v_mfma_f32_16x16x32_bf16 v[72:75], v[140:143], v[190:193], v[72:75]
	s_barrier
	s_mov_b32 s40, 0x1c000
	v_add_u32_e32 v152, s40, v170
	ds_read_b128 v[194:197], v152
	ds_read_b128 v[198:201], v152 offset:1024
	ds_read_b128 v[202:205], v152 offset:2048
	ds_read_b128 v[206:209], v152 offset:3072
	s_add_u32 s18, s14, 0x4000
	s_addc_u32 s19, s15, 0
	s_add_i32 s39, s39, s23
	s_mov_b32 m0, s39
	v_lshl_add_u64 v[210:211], s[18:19], 0, v[156:157]
	global_load_lds_dwordx4 v[210:211], off
	s_add_i32 m0, s39, 0x2000
	v_lshl_add_u64 v[210:211], s[18:19], 0, v[158:159]
	global_load_lds_dwordx4 v[210:211], off
	s_barrier
	s_waitcnt lgkmcnt(0)
	v_mfma_f32_16x16x32_bf16 v[116:119], v[194:197], v[144:147], v[116:119]
	s_setprio 1
	v_mfma_f32_16x16x32_bf16 v[112:115], v[202:205], v[144:147], v[112:115]
	s_mov_b32 m0, s29
	v_lshl_add_u64 v[210:211], s[16:17], 0, v[156:157]
	v_mfma_f32_16x16x32_bf16 v[100:103], v[194:197], v[166:169], v[100:103]
	v_mfma_f32_16x16x32_bf16 v[96:99], v[202:205], v[166:169], v[96:99]
	v_mfma_f32_16x16x32_bf16 v[84:87], v[194:197], v[178:181], v[84:87]
	v_mfma_f32_16x16x32_bf16 v[80:83], v[202:205], v[178:181], v[80:83]
	v_mfma_f32_16x16x32_bf16 v[68:71], v[194:197], v[186:189], v[68:71]
	v_mfma_f32_16x16x32_bf16 v[64:67], v[202:205], v[186:189], v[64:67]
	v_mfma_f32_16x16x32_bf16 v[116:119], v[198:201], v[148:151], v[116:119]
	v_mfma_f32_16x16x32_bf16 v[112:115], v[206:209], v[148:151], v[112:115]
	v_mfma_f32_16x16x32_bf16 v[100:103], v[198:201], v[174:177], v[100:103]
	v_mfma_f32_16x16x32_bf16 v[96:99], v[206:209], v[174:177], v[96:99]
	v_mfma_f32_16x16x32_bf16 v[84:87], v[198:201], v[182:185], v[84:87]
	v_mfma_f32_16x16x32_bf16 v[80:83], v[206:209], v[182:185], v[80:83]
	v_mfma_f32_16x16x32_bf16 v[68:71], v[198:201], v[190:193], v[68:71]
	s_setprio 0
	v_mfma_f32_16x16x32_bf16 v[64:67], v[206:209], v[190:193], v[64:67]
	s_barrier
	ds_read_b128 v[144:147], v172 offset:49152
	ds_read_b128 v[148:151], v172 offset:50176
	ds_read_b128 v[166:169], v172 offset:51200
	ds_read_b128 v[174:177], v172 offset:52224
	ds_read_b128 v[178:181], v172 offset:53248
	ds_read_b128 v[182:185], v172 offset:54272
	ds_read_b128 v[186:189], v172 offset:55296
	ds_read_b128 v[190:193], v172 offset:56320
	global_load_lds_dwordx4 v[210:211], off
	s_mov_b32 m0, s30
	v_lshl_add_u64 v[210:211], s[16:17], 0, v[158:159]
	global_load_lds_dwordx4 v[210:211], off
	s_barrier
; #define PG8_STAGE(bufoff, gbase, voff) do { _Pragma("unroll") for (int _i = 0; _i < 2; ++_i) \
;         __builtin_amdgcn_global_load_lds((const unsigned*)((const char*)(gbase) + (voff)[_i]), (LAS unsigned*)(lds + (bufoff) + ldsw + _i * 8192), 16, 0, 0); } while (0)
; #define PG8_MMA(ai, bj, At, Bt) do { __builtin_amdgcn_s_setprio(1); _Pragma("unroll") for (int m = 0; m < 4; ++m) _Pragma("unroll") for (int n = 0; n < 2; ++n) _Pragma("unroll") for (int k = 0; k < 2; ++k) \
;         acc[ai][bj][m][n] = __builtin_amdgcn_mfma_f32_16x16x32_bf16(Bt[n][k], At[m][k], acc[ai][bj][m][n], 0, 0, 0); __builtin_amdgcn_s_setprio(0); } while (0)
; #define PG8_WAIT_V(n) asm volatile("s_waitcnt vmcnt(" #n ")" ::: "memory")
; #define PG8_WAIT_L(n) asm volatile("s_waitcnt lgkmcnt(" #n ")" ::: "memory")
; #define PG8_BAR __builtin_amdgcn_s_barrier()
; #define PG8_SCHED __builtin_amdgcn_sched_barrier(0)
; template <class Epi>
; __device__ __forceinline__ void gemm_phase(LAS unsigned char* lds, const Gemm g, const StaticOrder& S, const Epi& E) {
;     ...
;             PG8_BAR; PG8_WAIT_L(0); PG8_MMA(1, 0, At, B0); PG8_BAR; PG8_SCHED;
;             PG8_STAGE(PG8_SB(1, 1), b3 + hstepB, voffB);
;             PG8_WAIT_V(6); PG8_BAR; PG8_MMA(1, 1, At, B1); PG8_BAR;
;     __device__ __forceinline__ void operator()(const f32x4 (&acc)[2][2][4][2], const Unit& u, int wr, int wc, int fr, int fq) const {
;         const int row0 = u.pm * BM + wr * 64 + fr, j0 = wc * 16 + 4 * fq, colb = u.pn * BM + j0;
;         if (u.pn < 8) {
	s_waitcnt lgkmcnt(0)
	v_mfma_f32_16x16x32_bf16 v[60:63], v[128:131], v[144:147], v[60:63]
	s_setprio 1
	v_mfma_f32_16x16x32_bf16 v[56:59], v[136:139], v[144:147], v[56:59]
	v_mfma_f32_16x16x32_bf16 v[44:47], v[128:131], v[166:169], v[44:47]
	v_mfma_f32_16x16x32_bf16 v[40:43], v[136:139], v[166:169], v[40:43]
	v_mfma_f32_16x16x32_bf16 v[28:31], v[128:131], v[178:181], v[28:31]
	v_mfma_f32_16x16x32_bf16 v[24:27], v[136:139], v[178:181], v[24:27]
	v_mfma_f32_16x16x32_bf16 v[12:15], v[128:131], v[186:189], v[12:15]
	v_mfma_f32_16x16x32_bf16 v[8:11], v[136:139], v[186:189], v[8:11]
	v_mfma_f32_16x16x32_bf16 v[60:63], v[132:135], v[148:151], v[60:63]
	v_mfma_f32_16x16x32_bf16 v[56:59], v[140:143], v[148:151], v[56:59]
	v_mfma_f32_16x16x32_bf16 v[44:47], v[132:135], v[174:177], v[44:47]
	v_mfma_f32_16x16x32_bf16 v[40:43], v[140:143], v[174:177], v[40:43]
	v_mfma_f32_16x16x32_bf16 v[28:31], v[132:135], v[182:185], v[28:31]
	v_mfma_f32_16x16x32_bf16 v[24:27], v[140:143], v[182:185], v[24:27]
	v_mfma_f32_16x16x32_bf16 v[12:15], v[132:135], v[190:193], v[12:15]
	s_setprio 0
	v_mfma_f32_16x16x32_bf16 v[8:11], v[140:143], v[190:193], v[8:11]
	s_barrier
	s_add_u32 s14, s14, 0x84000
	s_addc_u32 s15, s15, 0
	s_add_i32 s16, s40, s23
	s_mov_b32 m0, s16
	v_lshl_add_u64 v[128:129], s[14:15], 0, v[156:157]
	global_load_lds_dwordx4 v[128:129], off
	s_add_i32 m0, s16, 0x2000
	v_lshl_add_u64 v[128:129], s[14:15], 0, v[158:159]
	global_load_lds_dwordx4 v[128:129], off
	s_waitcnt vmcnt(6)
	s_barrier
	v_mfma_f32_16x16x32_bf16 v[52:55], v[194:197], v[144:147], v[52:55]
	s_setprio 1
	v_mfma_f32_16x16x32_bf16 v[48:51], v[202:205], v[144:147], v[48:51]
	s_add_i32 s38, s38, 2
	s_add_u32 s12, s12, 0x8000
	s_addc_u32 s13, s13, 0
	s_add_u32 s36, s36, 0x8000
	s_addc_u32 s37, s37, 0
	v_mfma_f32_16x16x32_bf16 v[36:39], v[194:197], v[166:169], v[36:39]
	v_mfma_f32_16x16x32_bf16 v[32:35], v[202:205], v[166:169], v[32:35]
	v_mfma_f32_16x16x32_bf16 v[20:23], v[194:197], v[178:181], v[20:23]
	v_mfma_f32_16x16x32_bf16 v[16:19], v[202:205], v[178:181], v[16:19]
	v_mfma_f32_16x16x32_bf16 v[4:7], v[194:197], v[186:189], v[4:7]
	v_mfma_f32_16x16x32_bf16 v[0:3], v[202:205], v[186:189], v[0:3]
	v_mfma_f32_16x16x32_bf16 v[52:55], v[198:201], v[148:151], v[52:55]
	v_mfma_f32_16x16x32_bf16 v[48:51], v[206:209], v[148:151], v[48:51]
	v_mfma_f32_16x16x32_bf16 v[36:39], v[198:201], v[174:177], v[36:39]
	v_mfma_f32_16x16x32_bf16 v[32:35], v[206:209], v[174:177], v[32:35]
	v_mfma_f32_16x16x32_bf16 v[20:23], v[198:201], v[182:185], v[20:23]
	v_mfma_f32_16x16x32_bf16 v[16:19], v[206:209], v[182:185], v[16:19]
	v_mfma_f32_16x16x32_bf16 v[4:7], v[198:201], v[190:193], v[4:7]
	s_cmp_gt_u32 s38, 29
	s_setprio 0
	v_mfma_f32_16x16x32_bf16 v[0:3], v[206:209], v[190:193], v[0:3]
	s_barrier
	s_cbranch_scc0 .LBB0_247
	v_lshl_add_u32 v177, s10, 8, v165
	v_lshl_or_b32 v152, s34, 8, v171
	s_mov_b64 s[10:11], -1
	s_cmp_lt_i32 s34, 8
	v_or_b32_e32 v180, 16, v177
	v_or_b32_e32 v179, 32, v177
	v_or_b32_e32 v178, 48, v177
	v_add_u32_e32 v176, 0x80, v177
	v_add_u32_e32 v175, 0x90, v177
	v_add_u32_e32 v174, 0xa0, v177
	v_add_u32_e32 v173, 0xb0, v177
	s_cbranch_scc1 .LBB0_250
; __device__ __forceinline__ unsigned cvt_pk_bf16(float lo, float hi) { unsigned r; asm volatile("v_cvt_pk_bf16_f32 %0, %1, %2" : "=v"(r) : "v"(lo), "v"(hi)); return r; }
;     __device__ __forceinline__ void operator()(const f32x4 (&acc)[2][2][4][2], const Unit& u, int wr, int wc, int fr, int fq) const {
;     ...
; #pragma unroll
;             for (int ai = 0; ai < 2; ++ai)
; #pragma unroll
;                 for (int m = 0; m < 4; ++m) {
;                     const int row = row0 + ai * HALF + m * 16;
;                     bf16_t* rowp = O + (size_t)row * DIN + colb;
; #pragma unroll
;                     for (int bj = 0; bj < 2; ++bj) {
;                         const f32x4 o1 = acc[ai][bj][m][0], o2 = acc[ai][bj][m][1];
;                         u32x2 w1, w2; w1.x = cvt_pk_bf16(o1[0], o1[1]); w1.y = cvt_pk_bf16(o1[2], o1[3]); w2.x = cvt_pk_bf16(o2[0], o2[1]); w2.y = cvt_pk_bf16(o2[2], o2[3]);
;                         *(u32x2*)(rowp + bj * HALF) = w1; *(u32x2*)(rowp + bj * HALF + 64) = w2;
;                     }
;                 }
	v_readlane_b32 s10, v252, 57
	v_readlane_b32 s11, v252, 58
	s_movk_i32 s3, 0x3000
	v_lshlrev_b64 v[130:131], 1, v[152:153]
	v_mov_b64_e32 v[128:129], s[10:11]
	v_mad_i64_i32 v[132:133], s[10:11], v177, s3, v[128:129]
	v_lshl_add_u64 v[132:133], v[132:133], 0, v[130:131]
	v_cvt_pk_bf16_f32 v134, v124, v125
	v_cvt_pk_bf16_f32 v135, v126, v127
	v_cvt_pk_bf16_f32 v136, v120, v121
	v_cvt_pk_bf16_f32 v137, v122, v123
	global_store_dwordx2 v[132:133], v[134:135], off
	global_store_dwordx2 v[132:133], v[136:137], off offset:128
	v_cvt_pk_bf16_f32 v134, v116, v117
	v_cvt_pk_bf16_f32 v135, v118, v119
	v_cvt_pk_bf16_f32 v136, v112, v113
	v_cvt_pk_bf16_f32 v137, v114, v115
	global_store_dwordx2 v[132:133], v[134:135], off offset:256
	global_store_dwordx2 v[132:133], v[136:137], off offset:384
	v_mad_i64_i32 v[132:133], s[10:11], v180, s3, v[128:129]
	v_lshl_add_u64 v[132:133], v[132:133], 0, v[130:131]
	v_cvt_pk_bf16_f32 v134, v108, v109
	v_cvt_pk_bf16_f32 v135, v110, v111
	v_cvt_pk_bf16_f32 v136, v104, v105
	v_cvt_pk_bf16_f32 v137, v106, v107
	global_store_dwordx2 v[132:133], v[134:135], off
	global_store_dwordx2 v[132:133], v[136:137], off offset:128
	v_cvt_pk_bf16_f32 v134, v100, v101
	v_cvt_pk_bf16_f32 v135, v102, v103
	v_cvt_pk_bf16_f32 v136, v96, v97
	v_cvt_pk_bf16_f32 v137, v98, v99
	global_store_dwordx2 v[132:133], v[134:135], off offset:256
	global_store_dwordx2 v[132:133], v[136:137], off offset:384
	v_mad_i64_i32 v[132:133], s[10:11], v179, s3, v[128:129]
	v_lshl_add_u64 v[132:133], v[132:133], 0, v[130:131]
	v_cvt_pk_bf16_f32 v134, v92, v93
	v_cvt_pk_bf16_f32 v135, v94, v95
	v_cvt_pk_bf16_f32 v136, v88, v89
	v_cvt_pk_bf16_f32 v137, v90, v91
	global_store_dwordx2 v[132:133], v[134:135], off
	global_store_dwordx2 v[132:133], v[136:137], off offset:128
	v_cvt_pk_bf16_f32 v134, v84, v85
	v_cvt_pk_bf16_f32 v135, v86, v87
	v_cvt_pk_bf16_f32 v136, v80, v81
	v_cvt_pk_bf16_f32 v137, v82, v83
	global_store_dwordx2 v[132:133], v[134:135], off offset:256
	global_store_dwordx2 v[132:133], v[136:137], off offset:384
	v_mad_i64_i32 v[132:133], s[10:11], v178, s3, v[128:129]
	v_lshl_add_u64 v[132:133], v[132:133], 0, v[130:131]
	v_cvt_pk_bf16_f32 v134, v76, v77
	v_cvt_pk_bf16_f32 v135, v78, v79
	v_cvt_pk_bf16_f32 v136, v72, v73
	v_cvt_pk_bf16_f32 v137, v74, v75
	global_store_dwordx2 v[132:133], v[134:135], off
	global_store_dwordx2 v[132:133], v[136:137], off offset:128
	v_cvt_pk_bf16_f32 v134, v68, v69
	v_cvt_pk_bf16_f32 v135, v70, v71
	v_cvt_pk_bf16_f32 v136, v64, v65
	v_cvt_pk_bf16_f32 v137, v66, v67
	global_store_dwordx2 v[132:133], v[134:135], off offset:256
	global_store_dwordx2 v[132:133], v[136:137], off offset:384
	v_mad_i64_i32 v[132:133], s[10:11], v176, s3, v[128:129]
	v_lshl_add_u64 v[132:133], v[132:133], 0, v[130:131]
	v_cvt_pk_bf16_f32 v134, v60, v61
	v_cvt_pk_bf16_f32 v135, v62, v63
	v_cvt_pk_bf16_f32 v136, v56, v57
	v_cvt_pk_bf16_f32 v137, v58, v59
	global_store_dwordx2 v[132:133], v[134:135], off
	global_store_dwordx2 v[132:133], v[136:137], off offset:128
	v_cvt_pk_bf16_f32 v134, v52, v53
	v_cvt_pk_bf16_f32 v135, v54, v55
	v_cvt_pk_bf16_f32 v136, v48, v49
	v_cvt_pk_bf16_f32 v137, v50, v51
	global_store_dwordx2 v[132:133], v[134:135], off offset:256
	global_store_dwordx2 v[132:133], v[136:137], off offset:384
	v_mad_i64_i32 v[132:133], s[10:11], v175, s3, v[128:129]
	v_lshl_add_u64 v[132:133], v[132:133], 0, v[130:131]
	v_cvt_pk_bf16_f32 v134, v44, v45
	v_cvt_pk_bf16_f32 v135, v46, v47
	v_cvt_pk_bf16_f32 v136, v40, v41
	v_cvt_pk_bf16_f32 v137, v42, v43
	global_store_dwordx2 v[132:133], v[134:135], off
	global_store_dwordx2 v[132:133], v[136:137], off offset:128
	v_cvt_pk_bf16_f32 v134, v36, v37
	v_cvt_pk_bf16_f32 v135, v38, v39
	v_cvt_pk_bf16_f32 v136, v32, v33
	v_cvt_pk_bf16_f32 v137, v34, v35
	global_store_dwordx2 v[132:133], v[134:135], off offset:256
	global_store_dwordx2 v[132:133], v[136:137], off offset:384
	v_mad_i64_i32 v[132:133], s[10:11], v174, s3, v[128:129]
	v_lshl_add_u64 v[132:133], v[132:133], 0, v[130:131]
	v_cvt_pk_bf16_f32 v134, v28, v29
	v_cvt_pk_bf16_f32 v135, v30, v31
	v_cvt_pk_bf16_f32 v136, v24, v25
	v_cvt_pk_bf16_f32 v137, v26, v27
	global_store_dwordx2 v[132:133], v[134:135], off
	global_store_dwordx2 v[132:133], v[136:137], off offset:128
	v_cvt_pk_bf16_f32 v134, v20, v21
	v_cvt_pk_bf16_f32 v135, v22, v23
	v_mad_i64_i32 v[128:129], s[10:11], v173, s3, v[128:129]
	v_cvt_pk_bf16_f32 v136, v16, v17
	v_cvt_pk_bf16_f32 v137, v18, v19
	global_store_dwordx2 v[132:133], v[134:135], off offset:256
	global_store_dwordx2 v[132:133], v[136:137], off offset:384
	v_lshl_add_u64 v[128:129], v[128:129], 0, v[130:131]
	v_cvt_pk_bf16_f32 v130, v12, v13
	v_cvt_pk_bf16_f32 v131, v14, v15
	v_cvt_pk_bf16_f32 v132, v8, v9
	v_cvt_pk_bf16_f32 v133, v10, v11
	s_mov_b64 s[10:11], 0
	global_store_dwordx2 v[128:129], v[130:131], off
	global_store_dwordx2 v[128:129], v[132:133], off offset:128
	v_cvt_pk_bf16_f32 v130, v4, v5
	v_cvt_pk_bf16_f32 v131, v6, v7
	v_cvt_pk_bf16_f32 v132, v0, v1
	v_cvt_pk_bf16_f32 v133, v2, v3
